# GEMM tile boundary: next tile's last first-iteration stage issued at the K-loop exit (ahead of the epilogue stores), first counted wait of the next tile relaxed to stores+8 (fc1, fc2, W_in GEMMs)
# baseline (speedup 1.0000x reference)
.LBB0_91:
	v_bfe_u32 v16, v6, 4, 2
	v_readlane_b32 s28, v254, 35
	v_and_b32_e32 v7, 15, v6
	v_lshlrev_b32_e32 v18, 4, v16
	v_lshlrev_b32_e32 v6, 2, v6
	v_readlane_b32 s29, v254, 36
	s_and_b32 s9, s0, 3
	v_lshl_or_b32 v174, s1, 6, v7
	v_lshl_or_b32 v7, v7, 6, v18
	s_lshl_b32 s0, s1, 13
	v_and_b32_e32 v6, 32, v6
	v_lshl_add_u64 v[8:9], s[28:29], 0, v[176:177]
	v_mov_b32_e32 v153, v177
	v_readlane_b32 s48, v254, 31
	v_bitop3_b32 v18, v7, s0, v6 bitop3:0xde
	s_lshl_b32 s0, s9, 12
	v_lshl_add_u64 v[10:11], s[28:29], 0, v[152:153]
	v_mov_b32_e32 v157, v177
	v_readlane_b32 s49, v254, 32
	v_bitop3_b32 v175, v7, s0, v6 bitop3:0xde
	s_add_i32 m0, s55, 0x18000
	v_lshl_add_u64 v[6:7], v[8:9], 0, s[52:53]
	v_lshl_add_u64 v[12:13], s[48:49], 0, v[156:157]
	v_mov_b32_e32 v155, v177
	s_waitcnt vmcnt(4)
	s_barrier
	global_load_lds_dwordx4 v[6:7], off
	v_lshl_add_u64 v[6:7], v[10:11], 0, s[52:53]
	s_add_i32 m0, s55, 0x1a000
	s_add_i32 s7, s55, 0x8000
	v_lshl_add_u64 v[14:15], s[48:49], 0, v[154:155]
	global_load_lds_dwordx4 v[6:7], off
	v_lshl_add_u64 v[6:7], v[12:13], 0, s[52:53]
	s_mov_b32 m0, s7
	s_add_i32 s15, s55, 0xa000
	v_readlane_b32 s0, v254, 37
	global_load_lds_dwordx4 v[6:7], off
	v_lshl_add_u64 v[6:7], v[14:15], 0, s[52:53]
	s_mov_b32 m0, s15
	v_readlane_b32 s1, v254, 38
	global_load_lds_dwordx4 v[6:7], off
	s_add_i32 m0, s55, 0x1c000
	v_lshl_add_u64 v[6:7], s[0:1], 0, v[176:177]
	global_load_lds_dwordx4 v[6:7], off
	v_lshl_add_u64 v[6:7], s[0:1], 0, v[152:153]
	s_add_i32 m0, s55, 0x1e000
	v_lshlrev_b32_e32 v17, 3, v16
	global_load_lds_dwordx4 v[6:7], off
	v_lshlrev_b32_e32 v6, 16, v4
	v_and_b32_e32 v6, 0xfffe0000, v6
	v_lshl_add_u32 v3, v3, 13, v6
	v_and_b32_e32 v4, 1, v4
	v_lshl_or_b32 v3, v4, 6, v3
	v_lshl_add_u32 v158, v5, 1, v3
	v_lshlrev_b32_e32 v3, 16, v0
	v_and_b32_e32 v3, 0xfffe0000, v3
	s_waitcnt vmcnt(6)
	v_lshl_add_u32 v1, v1, 13, v3
	v_and_b32_e32 v0, 1, v0
	v_lshl_or_b32 v0, v0, 6, v1
	v_readlane_b32 s0, v254, 39
	v_lshl_or_b32 v198, s9, 5, v17
	s_mov_b32 s6, 0
	v_cmp_eq_u32_e64 s[38:39], 0, v16
	s_waitcnt lgkmcnt(0)
	s_ashr_i32 s3, s59, 31
	v_mov_b32_e32 v159, v177
	v_lshl_add_u32 v160, v2, 1, v0
	v_mov_b32_e32 v161, v177
	v_add_u32_e32 v199, 0, v18
	v_readlane_b32 s34, v253, 59
	s_mov_b32 s2, s0
	s_barrier
	v_readlane_b32 s1, v254, 40
	s_mov_b32 s32, 0
	s_branch .LBB0_93

.LBB0_100:
	s_add_u32 s21, s48, 0xfff00080
	s_addc_u32 s28, s49, -1
	s_add_i32 s60, 0, 0x10000
	v_add_u32_e32 v124, s60, v175
	ds_read_b128 v[112:115], v124
	ds_read_b128 v[116:119], v124 offset:1024
	ds_read_b128 v[120:123], v124 offset:2048
	ds_read_b128 v[124:127], v124 offset:3072
	s_cmp_eq_u32 s20, 60
	s_cselect_b32 s51, s43, s28
	s_cselect_b32 s50, s24, s21
	s_cselect_b32 s29, s1, vcc_hi
	s_cselect_b32 s28, s25, vcc_lo
	s_add_i32 m0, s55, 0xc000
	ds_read_b128 v[128:131], v199
	ds_read_b128 v[132:135], v199 offset:1024
	ds_read_b128 v[162:165], v199 offset:2048
	ds_read_b128 v[166:169], v199 offset:3072
	ds_read_b128 v[170:173], v199 offset:4096
	ds_read_b128 v[200:203], v199 offset:5120
	ds_read_b128 v[204:207], v199 offset:6144
	ds_read_b128 v[208:211], v199 offset:7168
	global_load_lds_dwordx4 v158, s[48:49]
	s_add_i32 m0, s55, 0xe000
	s_nop 0
	global_load_lds_dwordx4 v160, s[48:49]
	s_waitcnt lgkmcnt(8)
	s_barrier
	s_waitcnt lgkmcnt(0)
	v_mfma_f32_16x16x32_bf16 v[148:151], v[112:115], v[128:131], v[148:151]
	v_mfma_f32_16x16x32_bf16 v[144:147], v[120:123], v[128:131], v[144:147]
	v_mfma_f32_16x16x32_bf16 v[108:111], v[112:115], v[162:165], v[108:111]
	v_mfma_f32_16x16x32_bf16 v[104:107], v[120:123], v[162:165], v[104:107]
	v_mfma_f32_16x16x32_bf16 v[92:95], v[112:115], v[170:173], v[92:95]
	v_mfma_f32_16x16x32_bf16 v[88:91], v[120:123], v[170:173], v[88:91]
	v_mfma_f32_16x16x32_bf16 v[76:79], v[112:115], v[204:207], v[76:79]
	v_mfma_f32_16x16x32_bf16 v[72:75], v[120:123], v[204:207], v[72:75]
	v_mfma_f32_16x16x32_bf16 v[148:151], v[116:119], v[132:135], v[148:151]
	v_mfma_f32_16x16x32_bf16 v[144:147], v[124:127], v[132:135], v[144:147]
	v_mfma_f32_16x16x32_bf16 v[108:111], v[116:119], v[166:169], v[108:111]
	v_mfma_f32_16x16x32_bf16 v[104:107], v[124:127], v[166:169], v[104:107]
	v_mfma_f32_16x16x32_bf16 v[92:95], v[116:119], v[200:203], v[92:95]
	v_mfma_f32_16x16x32_bf16 v[88:91], v[124:127], v[200:203], v[88:91]
	v_mfma_f32_16x16x32_bf16 v[76:79], v[116:119], v[208:211], v[76:79]
	v_mfma_f32_16x16x32_bf16 v[72:75], v[124:127], v[208:211], v[72:75]
	s_barrier
	s_add_i32 s21, 0, 0x14000
	v_add_u32_e32 v184, s21, v175
	s_add_i32 s60, s60, s54
	ds_read_b128 v[212:215], v184
	ds_read_b128 v[216:219], v184 offset:1024
	ds_read_b128 v[232:235], v184 offset:2048
	ds_read_b128 v[236:239], v184 offset:3072
	s_add_u32 s72, s28, s52
	s_addc_u32 s73, s29, s53
	s_mov_b32 m0, s60
	s_nop 0
	global_load_lds_dwordx4 v176, s[28:29]
	s_add_i32 m0, s60, 0x2000
	s_nop 0
	global_load_lds_dwordx4 v152, s[28:29]
	s_barrier
	s_waitcnt lgkmcnt(0)
	v_mfma_f32_16x16x32_bf16 v[140:143], v[212:215], v[128:131], v[140:143]
	v_mfma_f32_16x16x32_bf16 v[100:103], v[212:215], v[162:165], v[100:103]
	v_mfma_f32_16x16x32_bf16 v[96:99], v[232:235], v[162:165], v[96:99]
	v_mfma_f32_16x16x32_bf16 v[84:87], v[212:215], v[170:173], v[84:87]
	v_mfma_f32_16x16x32_bf16 v[80:83], v[232:235], v[170:173], v[80:83]
	v_mfma_f32_16x16x32_bf16 v[68:71], v[212:215], v[204:207], v[68:71]
	v_mfma_f32_16x16x32_bf16 v[64:67], v[232:235], v[204:207], v[64:67]
	v_mfma_f32_16x16x32_bf16 v[140:143], v[216:219], v[132:135], v[140:143]
	v_mfma_f32_16x16x32_bf16 v[128:131], v[232:235], v[128:131], v[136:139]
	v_mfma_f32_16x16x32_bf16 v[100:103], v[216:219], v[166:169], v[100:103]
	v_mfma_f32_16x16x32_bf16 v[96:99], v[236:239], v[166:169], v[96:99]
	v_mfma_f32_16x16x32_bf16 v[84:87], v[216:219], v[200:203], v[84:87]
	v_mfma_f32_16x16x32_bf16 v[80:83], v[236:239], v[200:203], v[80:83]
	v_mfma_f32_16x16x32_bf16 v[68:71], v[216:219], v[208:211], v[68:71]
	v_mfma_f32_16x16x32_bf16 v[64:67], v[236:239], v[208:211], v[64:67]
	v_mfma_f32_16x16x32_bf16 v[128:131], v[236:239], v[132:135], v[128:131]
	s_mov_b32 m0, s55
	s_add_u32 s94, s50, s52
	s_addc_u32 s95, s51, s53
	s_barrier
	ds_read_b128 v[132:135], v199 offset:16384
	ds_read_b128 v[136:139], v199 offset:17408
	ds_read_b128 v[162:165], v199 offset:18432
	ds_read_b128 v[166:169], v199 offset:19456
	ds_read_b128 v[170:173], v199 offset:20480
	ds_read_b128 v[200:203], v199 offset:21504
	ds_read_b128 v[204:207], v199 offset:22528
	ds_read_b128 v[208:211], v199 offset:23552
	global_load_lds_dwordx4 v156, s[50:51]
	s_mov_b32 m0, s56
	s_nop 0
	global_load_lds_dwordx4 v154, s[50:51]
	s_barrier
	s_waitcnt lgkmcnt(0)
	v_mfma_f32_16x16x32_bf16 v[60:63], v[112:115], v[132:135], v[60:63]
	v_mfma_f32_16x16x32_bf16 v[56:59], v[120:123], v[132:135], v[56:59]
	v_mfma_f32_16x16x32_bf16 v[44:47], v[112:115], v[162:165], v[44:47]
	v_mfma_f32_16x16x32_bf16 v[40:43], v[120:123], v[162:165], v[40:43]
	v_mfma_f32_16x16x32_bf16 v[28:31], v[112:115], v[170:173], v[28:31]
	v_mfma_f32_16x16x32_bf16 v[24:27], v[120:123], v[170:173], v[24:27]
	v_mfma_f32_16x16x32_bf16 v[12:15], v[112:115], v[204:207], v[12:15]
	v_mfma_f32_16x16x32_bf16 v[8:11], v[120:123], v[204:207], v[8:11]
	v_mfma_f32_16x16x32_bf16 v[60:63], v[116:119], v[136:139], v[60:63]
	v_mfma_f32_16x16x32_bf16 v[56:59], v[124:127], v[136:139], v[56:59]
	v_mfma_f32_16x16x32_bf16 v[44:47], v[116:119], v[166:169], v[44:47]
	v_mfma_f32_16x16x32_bf16 v[40:43], v[124:127], v[166:169], v[40:43]
	v_mfma_f32_16x16x32_bf16 v[28:31], v[116:119], v[200:203], v[28:31]
	v_mfma_f32_16x16x32_bf16 v[24:27], v[124:127], v[200:203], v[24:27]
	v_mfma_f32_16x16x32_bf16 v[12:15], v[116:119], v[208:211], v[12:15]
	v_mfma_f32_16x16x32_bf16 v[8:11], v[124:127], v[208:211], v[8:11]
	s_barrier
	s_add_u32 s60, s28, 0x100000
	s_addc_u32 s61, s29, 0
	s_add_i32 s21, s21, s54
	s_mov_b32 m0, s21
	s_nop 0
	global_load_lds_dwordx4 v176, s[60:61]
	s_add_i32 m0, s21, 0x2000
	s_nop 0
	global_load_lds_dwordx4 v152, s[60:61]
	s_cmp_lg_u32 s32, 0
	s_cbranch_scc1 .Lesa7_far
	s_waitcnt vmcnt(6)
.Lesa7_join:
	s_barrier
	v_mfma_f32_16x16x32_bf16 v[52:55], v[212:215], v[132:135], v[52:55]
	v_mfma_f32_16x16x32_bf16 v[48:51], v[232:235], v[132:135], v[48:51]
	v_mfma_f32_16x16x32_bf16 v[36:39], v[212:215], v[162:165], v[36:39]
	v_mfma_f32_16x16x32_bf16 v[32:35], v[232:235], v[162:165], v[32:35]
	v_mfma_f32_16x16x32_bf16 v[20:23], v[212:215], v[170:173], v[20:23]
	v_mfma_f32_16x16x32_bf16 v[16:19], v[232:235], v[170:173], v[16:19]
	v_mfma_f32_16x16x32_bf16 v[4:7], v[212:215], v[204:207], v[4:7]
	v_mfma_f32_16x16x32_bf16 v[0:3], v[232:235], v[204:207], v[0:3]
	v_mfma_f32_16x16x32_bf16 v[52:55], v[216:219], v[136:139], v[52:55]
	v_mfma_f32_16x16x32_bf16 v[48:51], v[236:239], v[136:139], v[48:51]
	v_mfma_f32_16x16x32_bf16 v[36:39], v[216:219], v[166:169], v[36:39]
	v_mfma_f32_16x16x32_bf16 v[32:35], v[236:239], v[166:169], v[32:35]
	v_mfma_f32_16x16x32_bf16 v[20:23], v[216:219], v[200:203], v[20:23]
	v_mfma_f32_16x16x32_bf16 v[16:19], v[236:239], v[200:203], v[16:19]
	v_mfma_f32_16x16x32_bf16 v[4:7], v[216:219], v[208:211], v[4:7]
	v_mfma_f32_16x16x32_bf16 v[0:3], v[236:239], v[208:211], v[0:3]
	s_add_i32 s21, 0, 0x18000
	v_add_u32_e32 v124, s21, v175
	s_barrier
	ds_read_b128 v[112:115], v124
	ds_read_b128 v[116:119], v124 offset:1024
	ds_read_b128 v[120:123], v124 offset:2048
	ds_read_b128 v[124:127], v124 offset:3072
	s_add_u32 s50, s50, 0x100000
	s_addc_u32 s51, s51, 0
	s_mov_b32 m0, s57
	ds_read_b128 v[132:135], v199 offset:32768
	ds_read_b128 v[136:139], v199 offset:33792
	ds_read_b128 v[162:165], v199 offset:34816
	ds_read_b128 v[166:169], v199 offset:35840
	ds_read_b128 v[170:173], v199 offset:36864
	ds_read_b128 v[200:203], v199 offset:37888
	ds_read_b128 v[204:207], v199 offset:38912
	ds_read_b128 v[208:211], v199 offset:39936
	global_load_lds_dwordx4 v156, s[50:51]
	s_mov_b32 m0, s58
	s_nop 0
	global_load_lds_dwordx4 v154, s[50:51]
	s_waitcnt lgkmcnt(8)
	s_barrier
	s_waitcnt lgkmcnt(0)
	v_mfma_f32_16x16x32_bf16 v[148:151], v[112:115], v[132:135], v[148:151]
	v_mfma_f32_16x16x32_bf16 v[144:147], v[120:123], v[132:135], v[144:147]
	v_mfma_f32_16x16x32_bf16 v[108:111], v[112:115], v[162:165], v[108:111]
	v_mfma_f32_16x16x32_bf16 v[104:107], v[120:123], v[162:165], v[104:107]
	v_mfma_f32_16x16x32_bf16 v[92:95], v[112:115], v[170:173], v[92:95]
	v_mfma_f32_16x16x32_bf16 v[88:91], v[120:123], v[170:173], v[88:91]
	v_mfma_f32_16x16x32_bf16 v[76:79], v[112:115], v[204:207], v[76:79]
	v_mfma_f32_16x16x32_bf16 v[72:75], v[120:123], v[204:207], v[72:75]
	v_mfma_f32_16x16x32_bf16 v[148:151], v[116:119], v[136:139], v[148:151]
	v_mfma_f32_16x16x32_bf16 v[144:147], v[124:127], v[136:139], v[144:147]
	v_mfma_f32_16x16x32_bf16 v[108:111], v[116:119], v[166:169], v[108:111]
	v_mfma_f32_16x16x32_bf16 v[104:107], v[124:127], v[166:169], v[104:107]
	v_mfma_f32_16x16x32_bf16 v[92:95], v[116:119], v[200:203], v[92:95]
	v_mfma_f32_16x16x32_bf16 v[88:91], v[124:127], v[200:203], v[88:91]
	v_mfma_f32_16x16x32_bf16 v[76:79], v[116:119], v[208:211], v[76:79]
	v_mfma_f32_16x16x32_bf16 v[72:75], v[124:127], v[208:211], v[72:75]
	s_barrier
	s_add_i32 s50, 0, 0x1c000
	s_add_i32 s21, s21, s54
	v_add_u32_e32 v231, s50, v175
	s_mov_b32 m0, s21
	ds_read_b128 v[212:215], v231
	ds_read_b128 v[216:219], v231 offset:1024
	ds_read_b128 v[232:235], v231 offset:2048
	ds_read_b128 v[236:239], v231 offset:3072
	global_load_lds_dwordx4 v176, s[72:73]
	s_add_i32 m0, s21, 0x2000
	s_nop 0
	global_load_lds_dwordx4 v152, s[72:73]
	s_barrier
	s_waitcnt lgkmcnt(0)
	v_mfma_f32_16x16x32_bf16 v[140:143], v[212:215], v[132:135], v[140:143]
	v_mfma_f32_16x16x32_bf16 v[128:131], v[232:235], v[132:135], v[128:131]
	v_mfma_f32_16x16x32_bf16 v[100:103], v[212:215], v[162:165], v[100:103]
	v_mfma_f32_16x16x32_bf16 v[96:99], v[232:235], v[162:165], v[96:99]
	v_mfma_f32_16x16x32_bf16 v[84:87], v[212:215], v[170:173], v[84:87]
	v_mfma_f32_16x16x32_bf16 v[80:83], v[232:235], v[170:173], v[80:83]
	v_mfma_f32_16x16x32_bf16 v[68:71], v[212:215], v[204:207], v[68:71]
	v_mfma_f32_16x16x32_bf16 v[64:67], v[232:235], v[204:207], v[64:67]
	v_mfma_f32_16x16x32_bf16 v[140:143], v[216:219], v[136:139], v[140:143]
	v_mfma_f32_16x16x32_bf16 v[136:139], v[236:239], v[136:139], v[128:131]
	v_mfma_f32_16x16x32_bf16 v[100:103], v[216:219], v[166:169], v[100:103]
	v_mfma_f32_16x16x32_bf16 v[96:99], v[236:239], v[166:169], v[96:99]
	v_mfma_f32_16x16x32_bf16 v[84:87], v[216:219], v[200:203], v[84:87]
	v_mfma_f32_16x16x32_bf16 v[80:83], v[236:239], v[200:203], v[80:83]
	v_mfma_f32_16x16x32_bf16 v[68:71], v[216:219], v[208:211], v[68:71]
	v_mfma_f32_16x16x32_bf16 v[64:67], v[236:239], v[208:211], v[64:67]
	s_mov_b32 m0, s7
	s_barrier
	ds_read_b128 v[128:131], v199 offset:49152
	ds_read_b128 v[132:135], v199 offset:50176
	ds_read_b128 v[162:165], v199 offset:51200
	ds_read_b128 v[166:169], v199 offset:52224
	ds_read_b128 v[170:173], v199 offset:53248
	ds_read_b128 v[200:203], v199 offset:54272
	ds_read_b128 v[204:207], v199 offset:55296
	ds_read_b128 v[208:211], v199 offset:56320
	global_load_lds_dwordx4 v156, s[94:95]
	s_mov_b32 m0, s15
	s_nop 0
	global_load_lds_dwordx4 v154, s[94:95]
	s_barrier
	s_waitcnt lgkmcnt(0)
	v_mfma_f32_16x16x32_bf16 v[60:63], v[112:115], v[128:131], v[60:63]
	v_mfma_f32_16x16x32_bf16 v[56:59], v[120:123], v[128:131], v[56:59]
	v_mfma_f32_16x16x32_bf16 v[44:47], v[112:115], v[162:165], v[44:47]
	v_mfma_f32_16x16x32_bf16 v[40:43], v[120:123], v[162:165], v[40:43]
	v_mfma_f32_16x16x32_bf16 v[28:31], v[112:115], v[170:173], v[28:31]
	v_mfma_f32_16x16x32_bf16 v[24:27], v[120:123], v[170:173], v[24:27]
	v_mfma_f32_16x16x32_bf16 v[12:15], v[112:115], v[204:207], v[12:15]
	v_mfma_f32_16x16x32_bf16 v[8:11], v[120:123], v[204:207], v[8:11]
	v_mfma_f32_16x16x32_bf16 v[60:63], v[116:119], v[132:135], v[60:63]
	v_mfma_f32_16x16x32_bf16 v[56:59], v[124:127], v[132:135], v[56:59]
	v_mfma_f32_16x16x32_bf16 v[44:47], v[116:119], v[166:169], v[44:47]
	v_mfma_f32_16x16x32_bf16 v[40:43], v[124:127], v[166:169], v[40:43]
	v_mfma_f32_16x16x32_bf16 v[28:31], v[116:119], v[200:203], v[28:31]
	v_mfma_f32_16x16x32_bf16 v[24:27], v[124:127], v[200:203], v[24:27]
	v_mfma_f32_16x16x32_bf16 v[12:15], v[116:119], v[208:211], v[12:15]
	v_mfma_f32_16x16x32_bf16 v[8:11], v[124:127], v[208:211], v[8:11]
	s_barrier
	s_add_u32 s28, s28, 0x100080
	s_addc_u32 s29, s29, 0
	s_add_i32 s21, s50, s54
	s_mov_b32 m0, s21
	s_nop 0
	global_load_lds_dwordx4 v176, s[28:29]
	s_add_i32 m0, s21, 0x2000
	s_nop 0
	global_load_lds_dwordx4 v152, s[28:29]
	s_waitcnt vmcnt(6)
	s_barrier
	v_mfma_f32_16x16x32_bf16 v[52:55], v[212:215], v[128:131], v[52:55]
	v_mfma_f32_16x16x32_bf16 v[48:51], v[232:235], v[128:131], v[48:51]
	v_mfma_f32_16x16x32_bf16 v[36:39], v[212:215], v[162:165], v[36:39]
	v_mfma_f32_16x16x32_bf16 v[32:35], v[232:235], v[162:165], v[32:35]
	v_mfma_f32_16x16x32_bf16 v[20:23], v[212:215], v[170:173], v[20:23]
	v_mfma_f32_16x16x32_bf16 v[16:19], v[232:235], v[170:173], v[16:19]
	v_mfma_f32_16x16x32_bf16 v[4:7], v[212:215], v[204:207], v[4:7]
	v_mfma_f32_16x16x32_bf16 v[0:3], v[232:235], v[204:207], v[0:3]
	v_mfma_f32_16x16x32_bf16 v[52:55], v[216:219], v[132:135], v[52:55]
	v_mfma_f32_16x16x32_bf16 v[48:51], v[236:239], v[132:135], v[48:51]
	v_mfma_f32_16x16x32_bf16 v[36:39], v[216:219], v[166:169], v[36:39]
	v_mfma_f32_16x16x32_bf16 v[32:35], v[236:239], v[166:169], v[32:35]
	v_mfma_f32_16x16x32_bf16 v[20:23], v[216:219], v[200:203], v[20:23]
	v_mfma_f32_16x16x32_bf16 v[16:19], v[236:239], v[200:203], v[16:19]
	v_mfma_f32_16x16x32_bf16 v[4:7], v[216:219], v[208:211], v[4:7]
	v_mfma_f32_16x16x32_bf16 v[0:3], v[236:239], v[208:211], v[0:3]
	s_add_i32 s20, s20, 2
	s_add_u32 s48, s48, 0x100
	s_addc_u32 s49, s49, 0
	s_add_u32 vcc_lo, vcc_lo, 0x100
	s_addc_u32 vcc_hi, vcc_hi, 0
	s_cmp_gt_u32 s20, 61
	s_barrier
	s_cbranch_scc0 .LBB0_100
	s_add_u32 s60, s24, 0x100080
	s_addc_u32 s61, s43, 0
	s_add_i32 m0, s55, 0xc000
	s_mov_b32 s32, 1
	global_load_lds_dwordx4 v158, s[60:61]
	s_add_i32 m0, s55, 0xe000
	s_nop 0
	global_load_lds_dwordx4 v160, s[60:61]
	v_readlane_b32 s48, v252, 4
	v_readlane_b32 s49, v252, 5
	v_readlane_b32 s60, v252, 6
	v_readlane_b32 s61, v252, 7
	v_lshl_or_b32 v162, s34, 8, v198
	v_lshl_add_u32 v166, s2, 8, v174
	v_lshlrev_b32_e32 v163, 11, v166
	v_lshl_add_u32 v163, v162, 1, v163
	global_load_dwordx4 v[200:203], v163, s[68:69]
	global_load_dwordx4 v[204:207], v163, s[68:69] offset:256
	s_add_u32 s20, s68, 0x8000
	s_addc_u32 s21, s69, 0
	global_load_dwordx4 v[208:211], v163, s[20:21]
	global_load_dwordx4 v[212:215], v163, s[20:21] offset:256
	s_add_u32 s20, s68, 0x10000
	s_addc_u32 s21, s69, 0
	global_load_dwordx4 v[216:219], v163, s[20:21]
	global_load_dwordx4 v[232:235], v163, s[20:21] offset:256
	s_add_u32 s20, s68, 0x18000
	s_addc_u32 s21, s69, 0
	global_load_dwordx4 v[236:239], v163, s[20:21]
	global_load_dwordx4 v[240:243], v163, s[20:21] offset:256
	s_add_u32 s20, s68, 0x40000
	s_addc_u32 s21, s69, 0
	global_load_dwordx4 v[244:247], v163, s[20:21]
	global_load_dwordx4 v[248:251], v163, s[20:21] offset:256
	s_add_u32 s20, s68, 0x48000
	s_addc_u32 s21, s69, 0
	global_load_dwordx4 v[112:115], v163, s[20:21]
	global_load_dwordx4 v[116:119], v163, s[20:21] offset:256
	s_add_u32 s20, s68, 0x50000
	s_addc_u32 s21, s69, 0
	global_load_dwordx4 v[120:123], v163, s[20:21]
	global_load_dwordx4 v[124:127], v163, s[20:21] offset:256
	s_add_u32 s20, s68, 0x58000
	s_addc_u32 s21, s69, 0
	global_load_dwordx4 v[128:131], v163, s[20:21]
	global_load_dwordx4 v[132:135], v163, s[20:21] offset:256
	v_lshlrev_b32_e32 v164, 6, v166
	v_and_b32_e32 v165, 0x30, v225
	v_add_u32_e32 v165, v164, v165
	v_lshlrev_b32_e32 v167, 12, v166
	v_lshl_add_u32 v167, v162, 2, v167
	v_lshlrev_b32_e32 v168, 2, v162
	v_xor_b32_e32 v169, 16, v225
	v_xor_b32_e32 v170, 32, v225
	v_lshlrev_b32_e32 v169, 2, v169
	v_lshlrev_b32_e32 v170, 2, v170
	s_cmpk_gt_u32 s92, 0xff
	s_cbranch_scc1 .Lf2e_nox
	s_barrier

.LBB0_138:
	v_and_b32_e32 v7, 15, v6
	v_lshrrev_b32_e32 v6, 1, v6
	v_and_b32_e32 v16, 24, v6
	v_readlane_b32 s28, v254, 6
	v_lshlrev_b32_e32 v6, 1, v16
	v_lshlrev_b32_e32 v17, 2, v7
	s_lshl_b32 s1, s1, 5
	v_readlane_b32 s29, v254, 7
	v_lshl_or_b32 v204, s0, 6, v7
	v_lshl_or_b32 v6, v7, 6, v6
	s_lshl_b32 s2, s0, 13
	v_and_b32_e32 v7, 32, v17
	s_and_b32 s1, s1, 0x60
	v_lshl_add_u64 v[8:9], s[28:29], 0, v[176:177]
	v_mov_b32_e32 v145, v177
	v_readlane_b32 s20, v254, 2
	v_bitop3_b32 v18, v6, s2, v7 bitop3:0xde
	s_lshl_b32 s2, s1, 7
	v_lshl_add_u64 v[10:11], s[28:29], 0, v[144:145]
	v_mov_b32_e32 v149, v177
	v_readlane_b32 s21, v254, 3
	v_bitop3_b32 v205, v6, s2, v7 bitop3:0xde
	s_add_i32 m0, s57, 0x18000
	v_lshl_add_u64 v[6:7], v[8:9], 0, s[52:53]
	v_lshl_add_u64 v[12:13], s[20:21], 0, v[148:149]
	v_mov_b32_e32 v147, v177
	s_waitcnt vmcnt(4)
	s_barrier
	global_load_lds_dwordx4 v[6:7], off
	v_lshl_add_u64 v[6:7], v[10:11], 0, s[52:53]
	s_add_i32 m0, s57, 0x1a000
	s_add_i32 s3, s57, 0x8000
	v_lshl_add_u64 v[14:15], s[20:21], 0, v[146:147]
	global_load_lds_dwordx4 v[6:7], off
	v_lshl_add_u64 v[6:7], v[12:13], 0, s[52:53]
	s_mov_b32 m0, s3
	s_add_i32 s6, s57, 0xa000
	v_readlane_b32 s24, v254, 8
	global_load_lds_dwordx4 v[6:7], off
	v_lshl_add_u64 v[6:7], v[14:15], 0, s[52:53]
	s_mov_b32 m0, s6
	v_readlane_b32 s25, v254, 9
	global_load_lds_dwordx4 v[6:7], off
	s_add_i32 m0, s57, 0x1c000
	v_lshl_add_u64 v[6:7], s[24:25], 0, v[176:177]
	global_load_lds_dwordx4 v[6:7], off
	v_lshl_add_u64 v[6:7], s[24:25], 0, v[144:145]
	s_add_i32 m0, s57, 0x1e000
	s_lshl_b32 s0, s0, 8
	global_load_lds_dwordx4 v[6:7], off
	v_lshlrev_b32_e32 v6, 14, v4
	v_and_b32_e32 v6, 0xffff8000, v6
	v_lshl_add_u32 v3, v3, 11, v6
	v_and_b32_e32 v4, 1, v4
	v_lshl_or_b32 v3, v4, 6, v3
	s_add_i32 s0, s0, 0
	v_lshl_add_u32 v150, v5, 1, v3
	v_lshlrev_b32_e32 v3, 14, v0
	s_add_i32 s0, s0, 0x20000
	v_and_b32_e32 v3, 0xffff8000, v3
	s_waitcnt vmcnt(6)
	v_add_u32_e32 v206, s0, v17
	v_or_b32_e32 v207, s1, v16
	v_lshl_add_u32 v1, v1, 11, v3
	v_and_b32_e32 v0, 1, v0
	v_readlane_b32 s0, v253, 60
	v_lshl_or_b32 v0, v0, 6, v1
	v_readlane_b32 s1, v253, 61
	v_mov_b32_e32 v151, v177
	v_lshl_add_u32 v152, v2, 1, v0
	v_mov_b32_e32 v153, v177
	s_mov_b32 s59, 0
	v_add_u32_e32 v208, 0, v18
	v_readlane_b32 s55, v253, 58
	s_mov_b32 s2, s0
	s_mov_b64 s[0:1], s[20:21]
	s_barrier
	s_mov_b32 s32, 0
	s_branch .LBB0_140

.LBB0_147:
	s_add_u32 s21, s0, 0xfffc0080
	s_addc_u32 s28, s1, -1
	s_add_i32 s60, 0, 0x10000
	v_add_u32_e32 v140, s60, v205
	ds_read_b128 v[128:131], v140
	ds_read_b128 v[132:135], v140 offset:1024
	ds_read_b128 v[136:139], v140 offset:2048
	ds_read_b128 v[140:143], v140 offset:3072
	s_cmp_eq_u32 s20, 12
	s_cselect_b32 s49, s43, s28
	s_cselect_b32 s48, s24, s21
	s_cselect_b32 s29, s25, vcc_hi
	s_cselect_b32 s28, s41, vcc_lo
	s_add_i32 m0, s57, 0xc000
	ds_read_b128 v[154:157], v208
	ds_read_b128 v[158:161], v208 offset:1024
	ds_read_b128 v[162:165], v208 offset:2048
	ds_read_b128 v[166:169], v208 offset:3072
	ds_read_b128 v[170:173], v208 offset:4096
	ds_read_b128 v[198:201], v208 offset:5120
	ds_read_b128 v[210:213], v208 offset:6144
	ds_read_b128 v[214:217], v208 offset:7168
	global_load_lds_dwordx4 v150, s[0:1]
	s_add_i32 m0, s57, 0xe000
	s_nop 0
	global_load_lds_dwordx4 v152, s[0:1]
	s_waitcnt lgkmcnt(8)
	s_barrier
	s_waitcnt lgkmcnt(0)
	v_mfma_f32_16x16x32_bf16 v[124:127], v[128:131], v[154:157], v[124:127]
	v_mfma_f32_16x16x32_bf16 v[120:123], v[136:139], v[154:157], v[120:123]
	v_mfma_f32_16x16x32_bf16 v[108:111], v[128:131], v[162:165], v[108:111]
	v_mfma_f32_16x16x32_bf16 v[104:107], v[136:139], v[162:165], v[104:107]
	v_mfma_f32_16x16x32_bf16 v[92:95], v[128:131], v[170:173], v[92:95]
	v_mfma_f32_16x16x32_bf16 v[88:91], v[136:139], v[170:173], v[88:91]
	v_mfma_f32_16x16x32_bf16 v[76:79], v[128:131], v[210:213], v[76:79]
	v_mfma_f32_16x16x32_bf16 v[72:75], v[136:139], v[210:213], v[72:75]
	v_mfma_f32_16x16x32_bf16 v[124:127], v[132:135], v[158:161], v[124:127]
	v_mfma_f32_16x16x32_bf16 v[120:123], v[140:143], v[158:161], v[120:123]
	v_mfma_f32_16x16x32_bf16 v[108:111], v[132:135], v[166:169], v[108:111]
	v_mfma_f32_16x16x32_bf16 v[104:107], v[140:143], v[166:169], v[104:107]
	v_mfma_f32_16x16x32_bf16 v[92:95], v[132:135], v[198:201], v[92:95]
	v_mfma_f32_16x16x32_bf16 v[88:91], v[140:143], v[198:201], v[88:91]
	v_mfma_f32_16x16x32_bf16 v[76:79], v[132:135], v[214:217], v[76:79]
	v_mfma_f32_16x16x32_bf16 v[72:75], v[140:143], v[214:217], v[72:75]
	s_barrier
	s_add_i32 s21, 0, 0x14000
	v_add_u32_e32 v174, s21, v205
	s_add_i32 s60, s60, s56
	ds_read_b128 v[232:235], v174
	ds_read_b128 v[236:239], v174 offset:1024
	ds_read_b128 v[240:243], v174 offset:2048
	ds_read_b128 v[244:247], v174 offset:3072
	s_add_u32 s72, s28, s52
	s_addc_u32 s73, s29, s53
	s_mov_b32 m0, s60
	s_nop 0
	global_load_lds_dwordx4 v176, s[28:29]
	s_add_i32 m0, s60, 0x2000
	s_nop 0
	global_load_lds_dwordx4 v144, s[28:29]
	s_barrier
	s_waitcnt lgkmcnt(0)
	v_mfma_f32_16x16x32_bf16 v[116:119], v[232:235], v[154:157], v[116:119]
	v_mfma_f32_16x16x32_bf16 v[112:115], v[240:243], v[154:157], v[112:115]
	v_mfma_f32_16x16x32_bf16 v[100:103], v[232:235], v[162:165], v[100:103]
	v_mfma_f32_16x16x32_bf16 v[96:99], v[240:243], v[162:165], v[96:99]
	v_mfma_f32_16x16x32_bf16 v[84:87], v[232:235], v[170:173], v[84:87]
	v_mfma_f32_16x16x32_bf16 v[80:83], v[240:243], v[170:173], v[80:83]
	v_mfma_f32_16x16x32_bf16 v[68:71], v[232:235], v[210:213], v[68:71]
	v_mfma_f32_16x16x32_bf16 v[64:67], v[240:243], v[210:213], v[64:67]
	v_mfma_f32_16x16x32_bf16 v[116:119], v[236:239], v[158:161], v[116:119]
	v_mfma_f32_16x16x32_bf16 v[112:115], v[244:247], v[158:161], v[112:115]
	v_mfma_f32_16x16x32_bf16 v[100:103], v[236:239], v[166:169], v[100:103]
	v_mfma_f32_16x16x32_bf16 v[96:99], v[244:247], v[166:169], v[96:99]
	v_mfma_f32_16x16x32_bf16 v[84:87], v[236:239], v[198:201], v[84:87]
	v_mfma_f32_16x16x32_bf16 v[80:83], v[244:247], v[198:201], v[80:83]
	v_mfma_f32_16x16x32_bf16 v[68:71], v[236:239], v[214:217], v[68:71]
	v_mfma_f32_16x16x32_bf16 v[64:67], v[244:247], v[214:217], v[64:67]
	s_mov_b32 m0, s57
	s_add_u32 s94, s48, s52
	s_addc_u32 s95, s49, s53
	s_barrier
	ds_read_b128 v[154:157], v208 offset:16384
	ds_read_b128 v[158:161], v208 offset:17408
	ds_read_b128 v[162:165], v208 offset:18432
	ds_read_b128 v[166:169], v208 offset:19456
	ds_read_b128 v[170:173], v208 offset:20480
	ds_read_b128 v[198:201], v208 offset:21504
	ds_read_b128 v[210:213], v208 offset:22528
	ds_read_b128 v[214:217], v208 offset:23552
	global_load_lds_dwordx4 v148, s[48:49]
	s_mov_b32 m0, s58
	s_nop 0
	global_load_lds_dwordx4 v146, s[48:49]
	s_barrier
	s_waitcnt lgkmcnt(0)
	v_mfma_f32_16x16x32_bf16 v[60:63], v[128:131], v[154:157], v[60:63]
	v_mfma_f32_16x16x32_bf16 v[56:59], v[136:139], v[154:157], v[56:59]
	v_mfma_f32_16x16x32_bf16 v[44:47], v[128:131], v[162:165], v[44:47]
	v_mfma_f32_16x16x32_bf16 v[40:43], v[136:139], v[162:165], v[40:43]
	v_mfma_f32_16x16x32_bf16 v[28:31], v[128:131], v[170:173], v[28:31]
	v_mfma_f32_16x16x32_bf16 v[24:27], v[136:139], v[170:173], v[24:27]
	v_mfma_f32_16x16x32_bf16 v[12:15], v[128:131], v[210:213], v[12:15]
	v_mfma_f32_16x16x32_bf16 v[8:11], v[136:139], v[210:213], v[8:11]
	v_mfma_f32_16x16x32_bf16 v[60:63], v[132:135], v[158:161], v[60:63]
	v_mfma_f32_16x16x32_bf16 v[56:59], v[140:143], v[158:161], v[56:59]
	v_mfma_f32_16x16x32_bf16 v[44:47], v[132:135], v[166:169], v[44:47]
	v_mfma_f32_16x16x32_bf16 v[40:43], v[140:143], v[166:169], v[40:43]
	v_mfma_f32_16x16x32_bf16 v[28:31], v[132:135], v[198:201], v[28:31]
	v_mfma_f32_16x16x32_bf16 v[24:27], v[140:143], v[198:201], v[24:27]
	v_mfma_f32_16x16x32_bf16 v[12:15], v[132:135], v[214:217], v[12:15]
	v_mfma_f32_16x16x32_bf16 v[8:11], v[140:143], v[214:217], v[8:11]
	s_barrier
	s_add_u32 s60, s28, 0x40000
	s_addc_u32 s61, s29, 0
	s_add_i32 s21, s21, s56
	s_mov_b32 m0, s21
	s_nop 0
	global_load_lds_dwordx4 v176, s[60:61]
	s_add_i32 m0, s21, 0x2000
	s_nop 0
	global_load_lds_dwordx4 v144, s[60:61]
	s_cmp_lg_u32 s32, 0
	s_cbranch_scc1 .Lesa6_far
	s_waitcnt vmcnt(6)
.Lesa6_join:
	s_barrier
	v_mfma_f32_16x16x32_bf16 v[52:55], v[232:235], v[154:157], v[52:55]
	v_mfma_f32_16x16x32_bf16 v[48:51], v[240:243], v[154:157], v[48:51]
	v_mfma_f32_16x16x32_bf16 v[36:39], v[232:235], v[162:165], v[36:39]
	v_mfma_f32_16x16x32_bf16 v[32:35], v[240:243], v[162:165], v[32:35]
	v_mfma_f32_16x16x32_bf16 v[20:23], v[232:235], v[170:173], v[20:23]
	v_mfma_f32_16x16x32_bf16 v[16:19], v[240:243], v[170:173], v[16:19]
	v_mfma_f32_16x16x32_bf16 v[4:7], v[232:235], v[210:213], v[4:7]
	v_mfma_f32_16x16x32_bf16 v[0:3], v[240:243], v[210:213], v[0:3]
	v_mfma_f32_16x16x32_bf16 v[52:55], v[236:239], v[158:161], v[52:55]
	v_mfma_f32_16x16x32_bf16 v[48:51], v[244:247], v[158:161], v[48:51]
	v_mfma_f32_16x16x32_bf16 v[36:39], v[236:239], v[166:169], v[36:39]
	v_mfma_f32_16x16x32_bf16 v[32:35], v[244:247], v[166:169], v[32:35]
	v_mfma_f32_16x16x32_bf16 v[20:23], v[236:239], v[198:201], v[20:23]
	v_mfma_f32_16x16x32_bf16 v[16:19], v[244:247], v[198:201], v[16:19]
	v_mfma_f32_16x16x32_bf16 v[4:7], v[236:239], v[214:217], v[4:7]
	v_mfma_f32_16x16x32_bf16 v[0:3], v[244:247], v[214:217], v[0:3]
	s_add_i32 s21, 0, 0x18000
	v_add_u32_e32 v140, s21, v205
	s_barrier
	ds_read_b128 v[128:131], v140
	ds_read_b128 v[132:135], v140 offset:1024
	ds_read_b128 v[136:139], v140 offset:2048
	ds_read_b128 v[140:143], v140 offset:3072
	s_add_u32 s48, s48, 0x40000
	s_addc_u32 s49, s49, 0
	s_mov_b32 m0, s7
	ds_read_b128 v[154:157], v208 offset:32768
	ds_read_b128 v[158:161], v208 offset:33792
	ds_read_b128 v[162:165], v208 offset:34816
	ds_read_b128 v[166:169], v208 offset:35840
	ds_read_b128 v[170:173], v208 offset:36864
	ds_read_b128 v[198:201], v208 offset:37888
	ds_read_b128 v[210:213], v208 offset:38912
	ds_read_b128 v[214:217], v208 offset:39936
	global_load_lds_dwordx4 v148, s[48:49]
	s_mov_b32 m0, s15
	s_nop 0
	global_load_lds_dwordx4 v146, s[48:49]
	s_waitcnt lgkmcnt(8)
	s_barrier
	s_waitcnt lgkmcnt(0)
	v_mfma_f32_16x16x32_bf16 v[124:127], v[128:131], v[154:157], v[124:127]
	v_mfma_f32_16x16x32_bf16 v[120:123], v[136:139], v[154:157], v[120:123]
	v_mfma_f32_16x16x32_bf16 v[108:111], v[128:131], v[162:165], v[108:111]
	v_mfma_f32_16x16x32_bf16 v[104:107], v[136:139], v[162:165], v[104:107]
	v_mfma_f32_16x16x32_bf16 v[92:95], v[128:131], v[170:173], v[92:95]
	v_mfma_f32_16x16x32_bf16 v[88:91], v[136:139], v[170:173], v[88:91]
	v_mfma_f32_16x16x32_bf16 v[76:79], v[128:131], v[210:213], v[76:79]
	v_mfma_f32_16x16x32_bf16 v[72:75], v[136:139], v[210:213], v[72:75]
	v_mfma_f32_16x16x32_bf16 v[124:127], v[132:135], v[158:161], v[124:127]
	v_mfma_f32_16x16x32_bf16 v[120:123], v[140:143], v[158:161], v[120:123]
	v_mfma_f32_16x16x32_bf16 v[108:111], v[132:135], v[166:169], v[108:111]
	v_mfma_f32_16x16x32_bf16 v[104:107], v[140:143], v[166:169], v[104:107]
	v_mfma_f32_16x16x32_bf16 v[92:95], v[132:135], v[198:201], v[92:95]
	v_mfma_f32_16x16x32_bf16 v[88:91], v[140:143], v[198:201], v[88:91]
	v_mfma_f32_16x16x32_bf16 v[76:79], v[132:135], v[214:217], v[76:79]
	v_mfma_f32_16x16x32_bf16 v[72:75], v[140:143], v[214:217], v[72:75]
	s_barrier
	s_add_i32 s48, 0, 0x1c000
	s_add_i32 s21, s21, s56
	v_add_u32_e32 v202, s48, v205
	s_mov_b32 m0, s21
	ds_read_b128 v[232:235], v202
	ds_read_b128 v[236:239], v202 offset:1024
	ds_read_b128 v[240:243], v202 offset:2048
	ds_read_b128 v[244:247], v202 offset:3072
	global_load_lds_dwordx4 v176, s[72:73]
	s_add_i32 m0, s21, 0x2000
	s_nop 0
	global_load_lds_dwordx4 v144, s[72:73]
	s_barrier
	s_waitcnt lgkmcnt(0)
	v_mfma_f32_16x16x32_bf16 v[116:119], v[232:235], v[154:157], v[116:119]
	v_mfma_f32_16x16x32_bf16 v[112:115], v[240:243], v[154:157], v[112:115]
	v_mfma_f32_16x16x32_bf16 v[100:103], v[232:235], v[162:165], v[100:103]
	v_mfma_f32_16x16x32_bf16 v[96:99], v[240:243], v[162:165], v[96:99]
	v_mfma_f32_16x16x32_bf16 v[84:87], v[232:235], v[170:173], v[84:87]
	v_mfma_f32_16x16x32_bf16 v[80:83], v[240:243], v[170:173], v[80:83]
	v_mfma_f32_16x16x32_bf16 v[68:71], v[232:235], v[210:213], v[68:71]
	v_mfma_f32_16x16x32_bf16 v[64:67], v[240:243], v[210:213], v[64:67]
	v_mfma_f32_16x16x32_bf16 v[116:119], v[236:239], v[158:161], v[116:119]
	v_mfma_f32_16x16x32_bf16 v[112:115], v[244:247], v[158:161], v[112:115]
	v_mfma_f32_16x16x32_bf16 v[100:103], v[236:239], v[166:169], v[100:103]
	v_mfma_f32_16x16x32_bf16 v[96:99], v[244:247], v[166:169], v[96:99]
	v_mfma_f32_16x16x32_bf16 v[84:87], v[236:239], v[198:201], v[84:87]
	v_mfma_f32_16x16x32_bf16 v[80:83], v[244:247], v[198:201], v[80:83]
	v_mfma_f32_16x16x32_bf16 v[68:71], v[236:239], v[214:217], v[68:71]
	v_mfma_f32_16x16x32_bf16 v[64:67], v[244:247], v[214:217], v[64:67]
	s_mov_b32 m0, s3
	s_barrier
	ds_read_b128 v[154:157], v208 offset:49152
	ds_read_b128 v[158:161], v208 offset:50176
	ds_read_b128 v[162:165], v208 offset:51200
	ds_read_b128 v[166:169], v208 offset:52224
	ds_read_b128 v[170:173], v208 offset:53248
	ds_read_b128 v[198:201], v208 offset:54272
	ds_read_b128 v[210:213], v208 offset:55296
	ds_read_b128 v[214:217], v208 offset:56320
	global_load_lds_dwordx4 v148, s[94:95]
	s_mov_b32 m0, s6
	s_nop 0
	global_load_lds_dwordx4 v146, s[94:95]
	s_barrier
	s_waitcnt lgkmcnt(0)
	v_mfma_f32_16x16x32_bf16 v[60:63], v[128:131], v[154:157], v[60:63]
	v_mfma_f32_16x16x32_bf16 v[56:59], v[136:139], v[154:157], v[56:59]
	v_mfma_f32_16x16x32_bf16 v[44:47], v[128:131], v[162:165], v[44:47]
	v_mfma_f32_16x16x32_bf16 v[40:43], v[136:139], v[162:165], v[40:43]
	v_mfma_f32_16x16x32_bf16 v[28:31], v[128:131], v[170:173], v[28:31]
	v_mfma_f32_16x16x32_bf16 v[24:27], v[136:139], v[170:173], v[24:27]
	v_mfma_f32_16x16x32_bf16 v[12:15], v[128:131], v[210:213], v[12:15]
	v_mfma_f32_16x16x32_bf16 v[8:11], v[136:139], v[210:213], v[8:11]
	v_mfma_f32_16x16x32_bf16 v[60:63], v[132:135], v[158:161], v[60:63]
	v_mfma_f32_16x16x32_bf16 v[56:59], v[140:143], v[158:161], v[56:59]
	v_mfma_f32_16x16x32_bf16 v[44:47], v[132:135], v[166:169], v[44:47]
	v_mfma_f32_16x16x32_bf16 v[40:43], v[140:143], v[166:169], v[40:43]
	v_mfma_f32_16x16x32_bf16 v[28:31], v[132:135], v[198:201], v[28:31]
	v_mfma_f32_16x16x32_bf16 v[24:27], v[140:143], v[198:201], v[24:27]
	v_mfma_f32_16x16x32_bf16 v[12:15], v[132:135], v[214:217], v[12:15]
	v_mfma_f32_16x16x32_bf16 v[8:11], v[140:143], v[214:217], v[8:11]
	s_barrier
	s_add_u32 s28, s28, 0x40080
	s_addc_u32 s29, s29, 0
	s_add_i32 s21, s48, s56
	s_mov_b32 m0, s21
	s_nop 0
	global_load_lds_dwordx4 v176, s[28:29]
	s_add_i32 m0, s21, 0x2000
	s_nop 0
	global_load_lds_dwordx4 v144, s[28:29]
	s_waitcnt vmcnt(6)
	s_barrier
	v_mfma_f32_16x16x32_bf16 v[52:55], v[232:235], v[154:157], v[52:55]
	v_mfma_f32_16x16x32_bf16 v[48:51], v[240:243], v[154:157], v[48:51]
	v_mfma_f32_16x16x32_bf16 v[36:39], v[232:235], v[162:165], v[36:39]
	v_mfma_f32_16x16x32_bf16 v[32:35], v[240:243], v[162:165], v[32:35]
	v_mfma_f32_16x16x32_bf16 v[20:23], v[232:235], v[170:173], v[20:23]
	v_mfma_f32_16x16x32_bf16 v[16:19], v[240:243], v[170:173], v[16:19]
	v_mfma_f32_16x16x32_bf16 v[4:7], v[232:235], v[210:213], v[4:7]
	v_mfma_f32_16x16x32_bf16 v[0:3], v[240:243], v[210:213], v[0:3]
	v_mfma_f32_16x16x32_bf16 v[52:55], v[236:239], v[158:161], v[52:55]
	v_mfma_f32_16x16x32_bf16 v[48:51], v[244:247], v[158:161], v[48:51]
	v_mfma_f32_16x16x32_bf16 v[36:39], v[236:239], v[166:169], v[36:39]
	v_mfma_f32_16x16x32_bf16 v[32:35], v[244:247], v[166:169], v[32:35]
	v_mfma_f32_16x16x32_bf16 v[20:23], v[236:239], v[198:201], v[20:23]
	v_mfma_f32_16x16x32_bf16 v[16:19], v[244:247], v[198:201], v[16:19]
	v_mfma_f32_16x16x32_bf16 v[4:7], v[236:239], v[214:217], v[4:7]
	v_mfma_f32_16x16x32_bf16 v[0:3], v[244:247], v[214:217], v[0:3]
	s_add_i32 s20, s20, 2
	s_add_u32 s0, s0, 0x100
	s_addc_u32 s1, s1, 0
	s_add_u32 vcc_lo, vcc_lo, 0x100
	s_addc_u32 vcc_hi, vcc_hi, 0
	s_cmp_gt_u32 s20, 13
	s_barrier
	s_cbranch_scc0 .LBB0_147
	s_add_u32 s60, s24, 0x40080
	s_addc_u32 s61, s43, 0
	s_add_i32 m0, s57, 0xc000
	s_mov_b32 s32, 1
	global_load_lds_dwordx4 v150, s[60:61]
	s_add_i32 m0, s57, 0xe000
	s_nop 0
	global_load_lds_dwordx4 v152, s[60:61]
	s_cmp_eq_u32 s2, s51
	s_cselect_b64 s[48:49], -1, 0
	s_cmp_eq_u32 s2, s50
	v_lshl_add_u32 v170, s2, 8, v204
	s_cselect_b64 s[0:1], -1, 0
	s_or_b64 s[20:21], s[48:49], s[0:1]
	v_or_b32_e32 v166, 16, v170
	v_or_b32_e32 v164, 32, v170
	v_or_b32_e32 v162, 48, v170
	v_add_u32_e32 v160, 0x80, v170
	v_add_u32_e32 v158, 0x90, v170
	v_add_u32_e32 v156, 0xa0, v170
	v_add_u32_e32 v154, 0xb0, v170
	s_mov_b64 s[0:1], -1
	s_and_b64 vcc, exec, s[20:21]
	v_ashrrev_i32_e32 v171, 31, v170
	v_ashrrev_i32_e32 v167, 31, v166
	v_ashrrev_i32_e32 v165, 31, v164
	v_ashrrev_i32_e32 v163, 31, v162
	v_ashrrev_i32_e32 v161, 31, v160
	v_ashrrev_i32_e32 v159, 31, v158
	v_ashrrev_i32_e32 v157, 31, v156
	v_ashrrev_i32_e32 v155, 31, v154
	s_cbranch_vccnz .LBB0_150
	v_readlane_b32 s20, v253, 31
	v_lshlrev_b64 v[128:129], 6, v[170:171]
	v_readlane_b32 s21, v253, 32
	s_mov_b32 s0, 0x3727c5ac
	v_mov_b64_e32 v[198:199], s[0:1]
	v_lshl_add_u64 v[140:141], s[20:21], 0, v[128:129]
	global_load_dwordx4 v[128:131], v[140:141], off offset:32
	global_load_dwordx4 v[132:135], v[140:141], off offset:48
	global_load_dwordx4 v[136:139], v[140:141], off
	s_nop 0
	global_load_dwordx4 v[140:143], v[140:141], off offset:16
	s_mov_b32 s2, 0x3a800000
	s_mov_b32 s24, 0x45800000
	s_waitcnt vmcnt(0)
	v_pk_add_f32 v[128:129], v[128:129], v[132:133]
	v_pk_add_f32 v[130:131], v[130:131], v[134:135]
	v_pk_add_f32 v[136:137], v[136:137], v[140:141]
	v_pk_add_f32 v[138:139], v[138:139], v[142:143]
	v_pk_add_f32 v[172:173], v[136:137], v[128:129]
	v_lshlrev_b64 v[128:129], 6, v[166:167]
	v_lshl_add_u64 v[140:141], s[20:21], 0, v[128:129]
	v_pk_add_f32 v[168:169], v[138:139], v[130:131]
	global_load_dwordx4 v[128:131], v[140:141], off offset:32
	global_load_dwordx4 v[132:135], v[140:141], off offset:48
	global_load_dwordx4 v[136:139], v[140:141], off
	s_nop 0
	global_load_dwordx4 v[140:143], v[140:141], off offset:16
	s_waitcnt vmcnt(0)
	v_pk_add_f32 v[128:129], v[128:129], v[132:133]
	v_pk_add_f32 v[130:131], v[130:131], v[134:135]
	v_pk_add_f32 v[136:137], v[136:137], v[140:141]
	v_pk_add_f32 v[138:139], v[138:139], v[142:143]
	v_pk_add_f32 v[128:129], v[136:137], v[128:129]
	v_pk_add_f32 v[130:131], v[138:139], v[130:131]
	v_mov_b32_e32 v132, v128
	v_mov_b32_e32 v133, v172
	v_mov_b32_e32 v172, v129
	v_pk_add_f32 v[128:129], v[132:133], v[172:173]
	v_mov_b32_e32 v132, v130
	v_mov_b32_e32 v133, v168
	v_pk_add_f32 v[128:129], v[132:133], v[128:129]
	v_mov_b32_e32 v168, v131
	v_pk_add_f32 v[128:129], v[168:169], v[128:129]
	s_nop 0
	v_pk_fma_f32 v[128:129], v[128:129], s[2:3], v[198:199] op_sel_hi:[1,0,0]
	s_nop 0
	v_mul_f32_e32 v130, 0x4b800000, v129
	v_cmp_gt_f32_e64 s[0:1], s23, v129
	v_cmp_gt_f32_e32 vcc, s23, v128
	s_nop 0
	v_cndmask_b32_e64 v129, v129, v130, s[0:1]
	v_mul_f32_e32 v130, 0x4b800000, v128
	v_cndmask_b32_e32 v128, v128, v130, vcc
	v_rsq_f32_e32 v129, v129
	v_rsq_f32_e32 v128, v128
	s_nop 0
	v_pk_mul_f32 v[130:131], v[128:129], s[24:25] op_sel_hi:[1,0]
	s_nop 0
	v_cndmask_b32_e32 v169, v128, v130, vcc
	v_cndmask_b32_e64 v168, v129, v131, s[0:1]
	v_lshlrev_b64 v[128:129], 6, v[164:165]
	v_lshl_add_u64 v[140:141], s[20:21], 0, v[128:129]
	global_load_dwordx4 v[128:131], v[140:141], off offset:32
	global_load_dwordx4 v[132:135], v[140:141], off offset:48
	global_load_dwordx4 v[136:139], v[140:141], off
	s_nop 0
	global_load_dwordx4 v[140:143], v[140:141], off offset:16
	s_waitcnt vmcnt(0)
	v_pk_add_f32 v[128:129], v[128:129], v[132:133]
	v_pk_add_f32 v[130:131], v[130:131], v[134:135]
	v_pk_add_f32 v[136:137], v[136:137], v[140:141]
	v_pk_add_f32 v[138:139], v[138:139], v[142:143]
	v_pk_add_f32 v[174:175], v[136:137], v[128:129]
	v_lshlrev_b64 v[128:129], 6, v[162:163]
	v_lshl_add_u64 v[140:141], s[20:21], 0, v[128:129]
	v_pk_add_f32 v[172:173], v[138:139], v[130:131]
	global_load_dwordx4 v[128:131], v[140:141], off offset:32
	global_load_dwordx4 v[132:135], v[140:141], off offset:48
	global_load_dwordx4 v[136:139], v[140:141], off
	s_nop 0
	global_load_dwordx4 v[140:143], v[140:141], off offset:16
	s_waitcnt vmcnt(0)
	v_pk_add_f32 v[128:129], v[128:129], v[132:133]
	v_pk_add_f32 v[130:131], v[130:131], v[134:135]
	v_pk_add_f32 v[136:137], v[136:137], v[140:141]
	v_pk_add_f32 v[138:139], v[138:139], v[142:143]
	v_pk_add_f32 v[128:129], v[136:137], v[128:129]
	v_pk_add_f32 v[130:131], v[138:139], v[130:131]
	v_mov_b32_e32 v132, v128
	v_mov_b32_e32 v133, v174
	v_mov_b32_e32 v174, v129
	v_pk_add_f32 v[128:129], v[132:133], v[174:175]
	v_mov_b32_e32 v132, v130
	v_mov_b32_e32 v133, v172
	v_pk_add_f32 v[128:129], v[132:133], v[128:129]
	v_mov_b32_e32 v172, v131
	v_pk_add_f32 v[128:129], v[172:173], v[128:129]
	s_nop 0
	v_pk_fma_f32 v[128:129], v[128:129], s[2:3], v[198:199] op_sel_hi:[1,0,0]
	s_nop 0
	v_mul_f32_e32 v130, 0x4b800000, v129
	v_cmp_gt_f32_e64 s[0:1], s23, v129
	v_cmp_gt_f32_e32 vcc, s23, v128
	s_nop 0
	v_cndmask_b32_e64 v129, v129, v130, s[0:1]
	v_mul_f32_e32 v130, 0x4b800000, v128
	v_cndmask_b32_e32 v128, v128, v130, vcc
	v_rsq_f32_e32 v129, v129
	v_rsq_f32_e32 v128, v128
	s_nop 0
	v_pk_mul_f32 v[130:131], v[128:129], s[24:25] op_sel_hi:[1,0]
	s_nop 0
	v_cndmask_b32_e32 v173, v128, v130, vcc
	v_cndmask_b32_e64 v172, v129, v131, s[0:1]
	v_lshlrev_b64 v[128:129], 6, v[160:161]
	v_lshl_add_u64 v[140:141], s[20:21], 0, v[128:129]
	global_load_dwordx4 v[128:131], v[140:141], off offset:32
	global_load_dwordx4 v[132:135], v[140:141], off offset:48
	global_load_dwordx4 v[136:139], v[140:141], off
	s_nop 0
	global_load_dwordx4 v[140:143], v[140:141], off offset:16
	s_waitcnt vmcnt(0)
	v_pk_add_f32 v[128:129], v[128:129], v[132:133]
	v_pk_add_f32 v[130:131], v[130:131], v[134:135]
	v_pk_add_f32 v[136:137], v[136:137], v[140:141]
	v_pk_add_f32 v[138:139], v[138:139], v[142:143]
	v_pk_add_f32 v[184:185], v[136:137], v[128:129]
	v_lshlrev_b64 v[128:129], 6, v[158:159]
	v_lshl_add_u64 v[140:141], s[20:21], 0, v[128:129]
	v_pk_add_f32 v[174:175], v[138:139], v[130:131]
	global_load_dwordx4 v[128:131], v[140:141], off offset:32
	global_load_dwordx4 v[132:135], v[140:141], off offset:48
	global_load_dwordx4 v[136:139], v[140:141], off
	s_nop 0
	global_load_dwordx4 v[140:143], v[140:141], off offset:16
	s_waitcnt vmcnt(0)
	v_pk_add_f32 v[128:129], v[128:129], v[132:133]
	v_pk_add_f32 v[130:131], v[130:131], v[134:135]
	v_pk_add_f32 v[136:137], v[136:137], v[140:141]
	v_pk_add_f32 v[138:139], v[138:139], v[142:143]
	v_pk_add_f32 v[128:129], v[136:137], v[128:129]
	v_pk_add_f32 v[130:131], v[138:139], v[130:131]
	v_mov_b32_e32 v132, v128
	v_mov_b32_e32 v133, v184
	v_mov_b32_e32 v184, v129
	v_pk_add_f32 v[128:129], v[132:133], v[184:185]
	v_mov_b32_e32 v132, v130
	v_mov_b32_e32 v133, v174
	v_pk_add_f32 v[128:129], v[132:133], v[128:129]
	v_mov_b32_e32 v174, v131
	v_pk_add_f32 v[128:129], v[174:175], v[128:129]
	s_nop 0
	v_pk_fma_f32 v[128:129], v[128:129], s[2:3], v[198:199] op_sel_hi:[1,0,0]
	s_nop 0
	v_mul_f32_e32 v130, 0x4b800000, v129
	v_cmp_gt_f32_e64 s[0:1], s23, v129
	v_cmp_gt_f32_e32 vcc, s23, v128
	s_nop 0
	v_cndmask_b32_e64 v129, v129, v130, s[0:1]
	v_mul_f32_e32 v130, 0x4b800000, v128
	v_cndmask_b32_e32 v128, v128, v130, vcc
	v_rsq_f32_e32 v129, v129
	v_rsq_f32_e32 v128, v128
	s_nop 0
	v_pk_mul_f32 v[130:131], v[128:129], s[24:25] op_sel_hi:[1,0]
	s_nop 0
	v_cndmask_b32_e32 v175, v128, v130, vcc
	v_cndmask_b32_e64 v174, v129, v131, s[0:1]
	v_lshlrev_b64 v[128:129], 6, v[156:157]
	v_lshl_add_u64 v[140:141], s[20:21], 0, v[128:129]
	global_load_dwordx4 v[128:131], v[140:141], off offset:32
	global_load_dwordx4 v[132:135], v[140:141], off offset:48
	global_load_dwordx4 v[136:139], v[140:141], off
	s_nop 0
	global_load_dwordx4 v[140:143], v[140:141], off offset:16
	s_waitcnt vmcnt(0)
	v_pk_add_f32 v[128:129], v[128:129], v[132:133]
	v_pk_add_f32 v[130:131], v[130:131], v[134:135]
	v_pk_add_f32 v[136:137], v[136:137], v[140:141]
	v_pk_add_f32 v[138:139], v[138:139], v[142:143]
	v_pk_add_f32 v[202:203], v[136:137], v[128:129]
	v_lshlrev_b64 v[128:129], 6, v[154:155]
	v_lshl_add_u64 v[140:141], s[20:21], 0, v[128:129]
	v_pk_add_f32 v[200:201], v[138:139], v[130:131]
	global_load_dwordx4 v[128:131], v[140:141], off offset:32
	global_load_dwordx4 v[132:135], v[140:141], off offset:48
	global_load_dwordx4 v[136:139], v[140:141], off
	s_nop 0
	global_load_dwordx4 v[140:143], v[140:141], off offset:16
	s_waitcnt vmcnt(0)
	v_pk_add_f32 v[128:129], v[128:129], v[132:133]
	v_pk_add_f32 v[130:131], v[130:131], v[134:135]
	v_pk_add_f32 v[136:137], v[136:137], v[140:141]
	v_pk_add_f32 v[138:139], v[138:139], v[142:143]
	v_pk_add_f32 v[128:129], v[136:137], v[128:129]
	v_pk_add_f32 v[130:131], v[138:139], v[130:131]
	v_mov_b32_e32 v132, v128
	v_mov_b32_e32 v133, v202
	v_mov_b32_e32 v202, v129
	v_pk_add_f32 v[128:129], v[132:133], v[202:203]
	v_mov_b32_e32 v132, v130
	v_mov_b32_e32 v133, v200
	v_pk_add_f32 v[128:129], v[132:133], v[128:129]
	v_mov_b32_e32 v200, v131
	v_pk_add_f32 v[128:129], v[200:201], v[128:129]
	s_nop 0
	v_pk_fma_f32 v[128:129], v[128:129], s[2:3], v[198:199] op_sel_hi:[1,0,0]
	s_nop 0
	v_mul_f32_e32 v130, 0x4b800000, v129
	v_cmp_gt_f32_e64 s[0:1], s23, v129
	v_cmp_gt_f32_e32 vcc, s23, v128
	s_nop 0
	v_cndmask_b32_e64 v129, v129, v130, s[0:1]
	v_rsq_f32_e32 v131, v129
	v_mul_f32_e32 v129, 0x4b800000, v128
	v_cndmask_b32_e32 v128, v128, v129, vcc
	v_rsq_f32_e32 v130, v128
	s_nop 0
	v_pk_mul_f32 v[132:133], v[130:131], s[24:25] op_sel_hi:[1,0]
	s_nop 0
	v_cndmask_b32_e32 v129, v130, v132, vcc
	v_cndmask_b32_e64 v128, v131, v133, s[0:1]
	s_mov_b64 s[0:1], 0

.LBB0_284:
	v_readlane_b32 s28, v254, 23
	v_readlane_b32 s29, v254, 24
	v_mov_b32_e32 v129, v177
	v_readlane_b32 s46, v254, 19
	v_lshl_add_u64 v[8:9], s[28:29], 0, v[176:177]
	v_lshl_add_u64 v[10:11], s[28:29], 0, v[128:129]
	v_mov_b32_e32 v133, v177
	v_readlane_b32 s47, v254, 20
	s_add_i32 m0, s7, 0x18000
	v_lshl_add_u64 v[8:9], v[8:9], 0, s[52:53]
	v_lshl_add_u64 v[12:13], s[46:47], 0, v[132:133]
	v_mov_b32_e32 v131, v177
	s_waitcnt vmcnt(4)
	s_barrier
	global_load_lds_dwordx4 v[8:9], off
	v_lshl_add_u64 v[8:9], v[10:11], 0, s[52:53]
	s_add_i32 m0, s7, 0x1a000
	s_add_i32 s51, s7, 0x8000
	v_lshl_add_u64 v[14:15], s[46:47], 0, v[130:131]
	global_load_lds_dwordx4 v[8:9], off
	v_lshl_add_u64 v[8:9], v[12:13], 0, s[52:53]
	s_mov_b32 m0, s51
	s_add_i32 s54, s7, 0xa000
	v_readlane_b32 s20, v254, 25
	global_load_lds_dwordx4 v[8:9], off
	v_lshl_add_u64 v[8:9], v[14:15], 0, s[52:53]
	s_mov_b32 m0, s54
	v_readlane_b32 s21, v254, 26
	global_load_lds_dwordx4 v[8:9], off
	s_add_i32 m0, s7, 0x1c000
	v_lshl_add_u64 v[8:9], s[20:21], 0, v[176:177]
	global_load_lds_dwordx4 v[8:9], off
	v_lshl_add_u64 v[8:9], s[20:21], 0, v[128:129]
	s_add_i32 m0, s7, 0x1e000
	v_and_b32_e32 v7, 15, v1
	global_load_lds_dwordx4 v[8:9], off
	v_lshrrev_b32_e32 v8, 1, v1
	v_and_b32_e32 v8, 24, v8
	v_lshlrev_b32_e32 v9, 1, v8
	v_lshlrev_b32_e32 v1, 2, v1
	s_lshl_b32 s0, s0, 5
	v_lshl_or_b32 v140, s1, 6, v7
	v_lshl_or_b32 v7, v7, 6, v9
	s_lshl_b32 s1, s1, 13
	v_and_b32_e32 v1, 32, v1
	s_and_b32 s0, s0, 0x60
	v_bitop3_b32 v9, v7, s1, v1 bitop3:0xde
	s_lshl_b32 s1, s0, 7
	v_bitop3_b32 v141, v7, s1, v1 bitop3:0xde
	v_lshlrev_b32_e32 v1, 14, v5
	v_and_b32_e32 v1, 0xffff8000, v1
	v_lshl_add_u32 v1, v4, 11, v1
	v_and_b32_e32 v4, 1, v5
	v_lshl_or_b32 v1, v4, 6, v1
	v_lshl_add_u32 v134, v6, 1, v1
	v_lshlrev_b32_e32 v1, 14, v0
	v_and_b32_e32 v1, 0xffff8000, v1
	s_waitcnt vmcnt(6)
	v_lshl_add_u32 v1, v2, 11, v1
	v_and_b32_e32 v0, 1, v0
	v_or_b32_e32 v142, s0, v8
	v_lshl_or_b32 v0, v0, 6, v1
	v_readlane_b32 s0, v254, 11
	s_waitcnt lgkmcnt(0)
	s_ashr_i32 s55, s50, 31
	v_mov_b32_e32 v135, v177
	v_lshl_add_u32 v136, v3, 1, v0
	v_mov_b32_e32 v137, v177
	s_mov_b32 s56, 0
	v_add_u32_e32 v143, 0, v9
	v_readlane_b32 s2, v254, 10
	s_mov_b32 s57, s0
	s_barrier
	v_readlane_b32 s1, v254, 12
	s_waitcnt vmcnt(0)
	s_mov_b32 s32, 0

.LBB0_292:
	s_add_u32 s20, s46, 0xfffc0080
	s_addc_u32 s21, s47, -1
	s_add_i32 s60, 0, 0x10000
	v_add_u32_e32 v138, s60, v141
	ds_read_b128 v[144:147], v138
	ds_read_b128 v[148:151], v138 offset:1024
	ds_read_b128 v[152:155], v138 offset:2048
	ds_read_b128 v[156:159], v138 offset:3072
	s_cmp_eq_u32 vcc_lo, 12
	s_cselect_b32 s49, s41, s21
	s_cselect_b32 s48, s24, s20
	s_cselect_b32 s29, s1, s59
	s_cselect_b32 s28, s25, s58
	s_add_i32 m0, s7, 0xc000
	ds_read_b128 v[160:163], v143
	ds_read_b128 v[164:167], v143 offset:1024
	ds_read_b128 v[168:171], v143 offset:2048
	ds_read_b128 v[172:175], v143 offset:3072
	ds_read_b128 v[198:201], v143 offset:4096
	ds_read_b128 v[202:205], v143 offset:5120
	ds_read_b128 v[206:209], v143 offset:6144
	ds_read_b128 v[210:213], v143 offset:7168
	global_load_lds_dwordx4 v134, s[46:47]
	s_add_i32 m0, s7, 0xe000
	s_nop 0
	global_load_lds_dwordx4 v136, s[46:47]
	s_waitcnt lgkmcnt(8)
	s_barrier
	s_waitcnt lgkmcnt(0)
	v_mfma_f32_16x16x32_bf16 v[124:127], v[144:147], v[160:163], v[124:127]
	v_mfma_f32_16x16x32_bf16 v[120:123], v[152:155], v[160:163], v[120:123]
	v_mfma_f32_16x16x32_bf16 v[116:119], v[144:147], v[168:171], v[116:119]
	v_mfma_f32_16x16x32_bf16 v[108:111], v[152:155], v[168:171], v[108:111]
	v_mfma_f32_16x16x32_bf16 v[100:103], v[144:147], v[198:201], v[100:103]
	v_mfma_f32_16x16x32_bf16 v[92:95], v[152:155], v[198:201], v[92:95]
	v_mfma_f32_16x16x32_bf16 v[80:83], v[144:147], v[206:209], v[80:83]
	v_mfma_f32_16x16x32_bf16 v[72:75], v[152:155], v[206:209], v[72:75]
	v_mfma_f32_16x16x32_bf16 v[124:127], v[148:151], v[164:167], v[124:127]
	v_mfma_f32_16x16x32_bf16 v[120:123], v[156:159], v[164:167], v[120:123]
	v_mfma_f32_16x16x32_bf16 v[116:119], v[148:151], v[172:175], v[116:119]
	v_mfma_f32_16x16x32_bf16 v[108:111], v[156:159], v[172:175], v[108:111]
	v_mfma_f32_16x16x32_bf16 v[100:103], v[148:151], v[202:205], v[100:103]
	v_mfma_f32_16x16x32_bf16 v[92:95], v[156:159], v[202:205], v[92:95]
	v_mfma_f32_16x16x32_bf16 v[80:83], v[148:151], v[210:213], v[80:83]
	v_mfma_f32_16x16x32_bf16 v[72:75], v[156:159], v[210:213], v[72:75]
	s_barrier
	s_add_i32 s61, 0, 0x14000
	v_add_u32_e32 v138, s61, v141
	s_add_i32 s20, s60, s6
	ds_read_b128 v[214:217], v138
	ds_read_b128 v[232:235], v138 offset:1024
	ds_read_b128 v[236:239], v138 offset:2048
	ds_read_b128 v[240:243], v138 offset:3072
	s_add_u32 s72, s28, s52
	s_addc_u32 s73, s29, s53
	s_mov_b32 m0, s20
	s_nop 0
	global_load_lds_dwordx4 v176, s[28:29]
	s_add_i32 m0, s20, 0x2000
	s_nop 0
	global_load_lds_dwordx4 v128, s[28:29]
	s_barrier
	s_waitcnt lgkmcnt(0)
	v_mfma_f32_16x16x32_bf16 v[112:115], v[214:217], v[160:163], v[112:115]
	v_mfma_f32_16x16x32_bf16 v[104:107], v[236:239], v[160:163], v[104:107]
	v_mfma_f32_16x16x32_bf16 v[96:99], v[214:217], v[168:171], v[96:99]
	v_mfma_f32_16x16x32_bf16 v[88:91], v[236:239], v[168:171], v[88:91]
	v_mfma_f32_16x16x32_bf16 v[84:87], v[214:217], v[198:201], v[84:87]
	v_mfma_f32_16x16x32_bf16 v[76:79], v[236:239], v[198:201], v[76:79]
	v_mfma_f32_16x16x32_bf16 v[68:71], v[214:217], v[206:209], v[68:71]
	v_mfma_f32_16x16x32_bf16 v[64:67], v[236:239], v[206:209], v[64:67]
	v_mfma_f32_16x16x32_bf16 v[112:115], v[232:235], v[164:167], v[112:115]
	v_mfma_f32_16x16x32_bf16 v[104:107], v[240:243], v[164:167], v[104:107]
	v_mfma_f32_16x16x32_bf16 v[96:99], v[232:235], v[172:175], v[96:99]
	v_mfma_f32_16x16x32_bf16 v[88:91], v[240:243], v[172:175], v[88:91]
	v_mfma_f32_16x16x32_bf16 v[84:87], v[232:235], v[202:205], v[84:87]
	v_mfma_f32_16x16x32_bf16 v[76:79], v[240:243], v[202:205], v[76:79]
	v_mfma_f32_16x16x32_bf16 v[68:71], v[232:235], v[210:213], v[68:71]
	v_mfma_f32_16x16x32_bf16 v[64:67], v[240:243], v[210:213], v[64:67]
	s_mov_b32 m0, s7
	s_add_u32 s94, s48, s52
	s_addc_u32 s95, s49, s53
	s_barrier
	ds_read_b128 v[160:163], v143 offset:16384
	ds_read_b128 v[164:167], v143 offset:17408
	ds_read_b128 v[168:171], v143 offset:18432
	ds_read_b128 v[172:175], v143 offset:19456
	ds_read_b128 v[198:201], v143 offset:20480
	ds_read_b128 v[202:205], v143 offset:21504
	ds_read_b128 v[206:209], v143 offset:22528
	ds_read_b128 v[210:213], v143 offset:23552
	global_load_lds_dwordx4 v132, s[48:49]
	s_mov_b32 m0, s9
	s_nop 0
	global_load_lds_dwordx4 v130, s[48:49]
	s_barrier
	s_waitcnt lgkmcnt(0)
	v_mfma_f32_16x16x32_bf16 v[60:63], v[144:147], v[160:163], v[60:63]
	v_mfma_f32_16x16x32_bf16 v[56:59], v[152:155], v[160:163], v[56:59]
	v_mfma_f32_16x16x32_bf16 v[52:55], v[144:147], v[168:171], v[52:55]
	v_mfma_f32_16x16x32_bf16 v[44:47], v[152:155], v[168:171], v[44:47]
	v_mfma_f32_16x16x32_bf16 v[36:39], v[144:147], v[198:201], v[36:39]
	v_mfma_f32_16x16x32_bf16 v[28:31], v[152:155], v[198:201], v[28:31]
	v_mfma_f32_16x16x32_bf16 v[20:23], v[144:147], v[206:209], v[20:23]
	v_mfma_f32_16x16x32_bf16 v[12:15], v[152:155], v[206:209], v[12:15]
	v_mfma_f32_16x16x32_bf16 v[60:63], v[148:151], v[164:167], v[60:63]
	v_mfma_f32_16x16x32_bf16 v[56:59], v[156:159], v[164:167], v[56:59]
	v_mfma_f32_16x16x32_bf16 v[52:55], v[148:151], v[172:175], v[52:55]
	v_mfma_f32_16x16x32_bf16 v[44:47], v[156:159], v[172:175], v[44:47]
	v_mfma_f32_16x16x32_bf16 v[36:39], v[148:151], v[202:205], v[36:39]
	v_mfma_f32_16x16x32_bf16 v[28:31], v[156:159], v[202:205], v[28:31]
	v_mfma_f32_16x16x32_bf16 v[20:23], v[148:151], v[210:213], v[20:23]
	v_mfma_f32_16x16x32_bf16 v[12:15], v[156:159], v[210:213], v[12:15]
	s_barrier
	s_add_u32 s20, s28, 0x40000
	s_addc_u32 s21, s29, 0
	s_add_i32 s60, s61, s6
	s_mov_b32 m0, s60
	s_nop 0
	global_load_lds_dwordx4 v176, s[20:21]
	s_add_i32 m0, s60, 0x2000
	s_nop 0
	global_load_lds_dwordx4 v128, s[20:21]
	s_cmp_lg_u32 s32, 0
	s_cbranch_scc1 .Lesa1_far
	s_waitcnt vmcnt(6)
.Lesa1_join:
	s_barrier
	v_mfma_f32_16x16x32_bf16 v[48:51], v[214:217], v[160:163], v[48:51]
	v_mfma_f32_16x16x32_bf16 v[40:43], v[236:239], v[160:163], v[40:43]
	v_mfma_f32_16x16x32_bf16 v[32:35], v[214:217], v[168:171], v[32:35]
	v_mfma_f32_16x16x32_bf16 v[24:27], v[236:239], v[168:171], v[24:27]
	v_mfma_f32_16x16x32_bf16 v[16:19], v[214:217], v[198:201], v[16:19]
	v_mfma_f32_16x16x32_bf16 v[8:11], v[236:239], v[198:201], v[8:11]
	v_mfma_f32_16x16x32_bf16 v[4:7], v[214:217], v[206:209], v[4:7]
	v_mfma_f32_16x16x32_bf16 v[0:3], v[236:239], v[206:209], v[0:3]
	v_mfma_f32_16x16x32_bf16 v[48:51], v[232:235], v[164:167], v[48:51]
	v_mfma_f32_16x16x32_bf16 v[40:43], v[240:243], v[164:167], v[40:43]
	v_mfma_f32_16x16x32_bf16 v[32:35], v[232:235], v[172:175], v[32:35]
	v_mfma_f32_16x16x32_bf16 v[24:27], v[240:243], v[172:175], v[24:27]
	v_mfma_f32_16x16x32_bf16 v[16:19], v[232:235], v[202:205], v[16:19]
	v_mfma_f32_16x16x32_bf16 v[8:11], v[240:243], v[202:205], v[8:11]
	v_mfma_f32_16x16x32_bf16 v[4:7], v[232:235], v[210:213], v[4:7]
	v_mfma_f32_16x16x32_bf16 v[0:3], v[240:243], v[210:213], v[0:3]
	s_add_i32 s60, 0, 0x18000
	v_add_u32_e32 v156, s60, v141
	s_barrier
	ds_read_b128 v[144:147], v156
	ds_read_b128 v[148:151], v156 offset:1024
	ds_read_b128 v[152:155], v156 offset:2048
	ds_read_b128 v[156:159], v156 offset:3072
	s_add_u32 s20, s48, 0x40000
	s_addc_u32 s21, s49, 0
	s_mov_b32 m0, s15
	ds_read_b128 v[160:163], v143 offset:32768
	ds_read_b128 v[164:167], v143 offset:33792
	ds_read_b128 v[168:171], v143 offset:34816
	ds_read_b128 v[172:175], v143 offset:35840
	ds_read_b128 v[198:201], v143 offset:36864
	ds_read_b128 v[202:205], v143 offset:37888
	ds_read_b128 v[206:209], v143 offset:38912
	ds_read_b128 v[210:213], v143 offset:39936
	global_load_lds_dwordx4 v132, s[20:21]
	s_mov_b32 m0, s34
	s_nop 0
	global_load_lds_dwordx4 v130, s[20:21]
	s_waitcnt lgkmcnt(8)
	s_barrier
	s_waitcnt lgkmcnt(0)
	v_mfma_f32_16x16x32_bf16 v[124:127], v[144:147], v[160:163], v[124:127]
	v_mfma_f32_16x16x32_bf16 v[120:123], v[152:155], v[160:163], v[120:123]
	v_mfma_f32_16x16x32_bf16 v[116:119], v[144:147], v[168:171], v[116:119]
	v_mfma_f32_16x16x32_bf16 v[108:111], v[152:155], v[168:171], v[108:111]
	v_mfma_f32_16x16x32_bf16 v[100:103], v[144:147], v[198:201], v[100:103]
	v_mfma_f32_16x16x32_bf16 v[92:95], v[152:155], v[198:201], v[92:95]
	v_mfma_f32_16x16x32_bf16 v[80:83], v[144:147], v[206:209], v[80:83]
	v_mfma_f32_16x16x32_bf16 v[72:75], v[152:155], v[206:209], v[72:75]
	v_mfma_f32_16x16x32_bf16 v[124:127], v[148:151], v[164:167], v[124:127]
	v_mfma_f32_16x16x32_bf16 v[120:123], v[156:159], v[164:167], v[120:123]
	v_mfma_f32_16x16x32_bf16 v[116:119], v[148:151], v[172:175], v[116:119]
	v_mfma_f32_16x16x32_bf16 v[108:111], v[156:159], v[172:175], v[108:111]
	v_mfma_f32_16x16x32_bf16 v[100:103], v[148:151], v[202:205], v[100:103]
	v_mfma_f32_16x16x32_bf16 v[92:95], v[156:159], v[202:205], v[92:95]
	v_mfma_f32_16x16x32_bf16 v[80:83], v[148:151], v[210:213], v[80:83]
	v_mfma_f32_16x16x32_bf16 v[72:75], v[156:159], v[210:213], v[72:75]
	s_barrier
	s_add_i32 s48, 0, 0x1c000
	s_add_i32 s20, s60, s6
	v_add_u32_e32 v184, s48, v141
	s_mov_b32 m0, s20
	ds_read_b128 v[214:217], v184
	ds_read_b128 v[232:235], v184 offset:1024
	ds_read_b128 v[236:239], v184 offset:2048
	ds_read_b128 v[240:243], v184 offset:3072
	global_load_lds_dwordx4 v176, s[72:73]
	s_add_i32 m0, s20, 0x2000
	s_nop 0
	global_load_lds_dwordx4 v128, s[72:73]
	s_barrier
	s_waitcnt lgkmcnt(0)
	v_mfma_f32_16x16x32_bf16 v[112:115], v[214:217], v[160:163], v[112:115]
	v_mfma_f32_16x16x32_bf16 v[104:107], v[236:239], v[160:163], v[104:107]
	v_mfma_f32_16x16x32_bf16 v[96:99], v[214:217], v[168:171], v[96:99]
	v_mfma_f32_16x16x32_bf16 v[88:91], v[236:239], v[168:171], v[88:91]
	v_mfma_f32_16x16x32_bf16 v[84:87], v[214:217], v[198:201], v[84:87]
	v_mfma_f32_16x16x32_bf16 v[76:79], v[236:239], v[198:201], v[76:79]
	v_mfma_f32_16x16x32_bf16 v[68:71], v[214:217], v[206:209], v[68:71]
	v_mfma_f32_16x16x32_bf16 v[64:67], v[236:239], v[206:209], v[64:67]
	v_mfma_f32_16x16x32_bf16 v[112:115], v[232:235], v[164:167], v[112:115]
	v_mfma_f32_16x16x32_bf16 v[104:107], v[240:243], v[164:167], v[104:107]
	v_mfma_f32_16x16x32_bf16 v[96:99], v[232:235], v[172:175], v[96:99]
	v_mfma_f32_16x16x32_bf16 v[88:91], v[240:243], v[172:175], v[88:91]
	v_mfma_f32_16x16x32_bf16 v[84:87], v[232:235], v[202:205], v[84:87]
	v_mfma_f32_16x16x32_bf16 v[76:79], v[240:243], v[202:205], v[76:79]
	v_mfma_f32_16x16x32_bf16 v[68:71], v[232:235], v[210:213], v[68:71]
	v_mfma_f32_16x16x32_bf16 v[64:67], v[240:243], v[210:213], v[64:67]
	s_mov_b32 m0, s51
	s_barrier
	ds_read_b128 v[160:163], v143 offset:49152
	ds_read_b128 v[164:167], v143 offset:50176
	ds_read_b128 v[168:171], v143 offset:51200
	ds_read_b128 v[172:175], v143 offset:52224
	ds_read_b128 v[198:201], v143 offset:53248
	ds_read_b128 v[202:205], v143 offset:54272
	ds_read_b128 v[206:209], v143 offset:55296
	ds_read_b128 v[210:213], v143 offset:56320
	global_load_lds_dwordx4 v132, s[94:95]
	s_mov_b32 m0, s54
	s_nop 0
	global_load_lds_dwordx4 v130, s[94:95]
	s_barrier
	s_waitcnt lgkmcnt(0)
	v_mfma_f32_16x16x32_bf16 v[60:63], v[144:147], v[160:163], v[60:63]
	v_mfma_f32_16x16x32_bf16 v[56:59], v[152:155], v[160:163], v[56:59]
	v_mfma_f32_16x16x32_bf16 v[52:55], v[144:147], v[168:171], v[52:55]
	v_mfma_f32_16x16x32_bf16 v[44:47], v[152:155], v[168:171], v[44:47]
	v_mfma_f32_16x16x32_bf16 v[36:39], v[144:147], v[198:201], v[36:39]
	v_mfma_f32_16x16x32_bf16 v[28:31], v[152:155], v[198:201], v[28:31]
	v_mfma_f32_16x16x32_bf16 v[20:23], v[144:147], v[206:209], v[20:23]
	v_mfma_f32_16x16x32_bf16 v[12:15], v[152:155], v[206:209], v[12:15]
	v_mfma_f32_16x16x32_bf16 v[60:63], v[148:151], v[164:167], v[60:63]
	v_mfma_f32_16x16x32_bf16 v[56:59], v[156:159], v[164:167], v[56:59]
	v_mfma_f32_16x16x32_bf16 v[52:55], v[148:151], v[172:175], v[52:55]
	v_mfma_f32_16x16x32_bf16 v[44:47], v[156:159], v[172:175], v[44:47]
	v_mfma_f32_16x16x32_bf16 v[36:39], v[148:151], v[202:205], v[36:39]
	v_mfma_f32_16x16x32_bf16 v[28:31], v[156:159], v[202:205], v[28:31]
	v_mfma_f32_16x16x32_bf16 v[20:23], v[148:151], v[210:213], v[20:23]
	v_mfma_f32_16x16x32_bf16 v[12:15], v[156:159], v[210:213], v[12:15]
	s_barrier
	s_add_u32 s20, s28, 0x40080
	s_addc_u32 s21, s29, 0
	s_add_i32 s28, s48, s6
	s_mov_b32 m0, s28
	s_nop 0
	global_load_lds_dwordx4 v176, s[20:21]
	s_add_i32 m0, s28, 0x2000
	s_nop 0
	global_load_lds_dwordx4 v128, s[20:21]
	s_waitcnt vmcnt(6)
	s_barrier
	v_mfma_f32_16x16x32_bf16 v[48:51], v[214:217], v[160:163], v[48:51]
	v_mfma_f32_16x16x32_bf16 v[40:43], v[236:239], v[160:163], v[40:43]
	v_mfma_f32_16x16x32_bf16 v[32:35], v[214:217], v[168:171], v[32:35]
	v_mfma_f32_16x16x32_bf16 v[24:27], v[236:239], v[168:171], v[24:27]
	v_mfma_f32_16x16x32_bf16 v[16:19], v[214:217], v[198:201], v[16:19]
	v_mfma_f32_16x16x32_bf16 v[8:11], v[236:239], v[198:201], v[8:11]
	v_mfma_f32_16x16x32_bf16 v[4:7], v[214:217], v[206:209], v[4:7]
	v_mfma_f32_16x16x32_bf16 v[0:3], v[236:239], v[206:209], v[0:3]
	v_mfma_f32_16x16x32_bf16 v[48:51], v[232:235], v[164:167], v[48:51]
	v_mfma_f32_16x16x32_bf16 v[40:43], v[240:243], v[164:167], v[40:43]
	v_mfma_f32_16x16x32_bf16 v[32:35], v[232:235], v[172:175], v[32:35]
	v_mfma_f32_16x16x32_bf16 v[24:27], v[240:243], v[172:175], v[24:27]
	v_mfma_f32_16x16x32_bf16 v[16:19], v[232:235], v[202:205], v[16:19]
	v_mfma_f32_16x16x32_bf16 v[8:11], v[240:243], v[202:205], v[8:11]
	v_mfma_f32_16x16x32_bf16 v[4:7], v[232:235], v[210:213], v[4:7]
	v_mfma_f32_16x16x32_bf16 v[0:3], v[240:243], v[210:213], v[0:3]
	s_add_i32 vcc_lo, vcc_lo, 2
	s_add_u32 s46, s46, 0x100
	s_addc_u32 s47, s47, 0
	s_add_u32 s58, s58, 0x100
	s_addc_u32 s59, s59, 0
	s_cmp_gt_u32 vcc_lo, 13
	s_barrier
	s_cbranch_scc0 .LBB0_292
	s_add_u32 s60, s24, 0x40080
	s_addc_u32 s61, s41, 0
	s_add_i32 m0, s7, 0xc000
	s_mov_b32 s32, 1
	global_load_lds_dwordx4 v134, s[60:61]
	s_add_i32 m0, s7, 0xe000
	s_nop 0
	global_load_lds_dwordx4 v136, s[60:61]
	v_lshl_add_u32 v144, s57, 8, v140
	v_lshl_or_b32 v138, s2, 8, v142
	v_ashrrev_i32_e32 v145, 31, v144
	v_readlane_b32 s20, v254, 43
	v_ashrrev_i32_e32 v139, 31, v138
	v_lshlrev_b64 v[146:147], 16, v[144:145]
	v_readlane_b32 s21, v254, 44
	v_lshlrev_b64 v[148:149], 1, v[138:139]
	v_cvt_pk_bf16_f32 v124, v124, v125
	v_cvt_pk_bf16_f32 v125, v126, v127
	v_cvt_pk_bf16_f32 v126, v120, v121
	v_cvt_pk_bf16_f32 v127, v122, v123
	s_nop 0
	v_lshl_add_u64 v[146:147], s[20:21], 0, v[146:147]
	v_lshl_add_u64 v[138:139], v[146:147], 0, v[148:149]
	global_store_dwordx4 v[138:139], v[124:127], off
	v_cvt_pk_bf16_f32 v112, v112, v113
	v_cvt_pk_bf16_f32 v113, v114, v115
	v_cvt_pk_bf16_f32 v114, v104, v105
	v_or_b32_e32 v104, 16, v144
	v_ashrrev_i32_e32 v105, 31, v104
	v_lshlrev_b64 v[104:105], 16, v[104:105]
	v_lshl_add_u64 v[104:105], s[20:21], 0, v[104:105]
	v_cvt_pk_bf16_f32 v115, v106, v107
	global_store_dwordx4 v[138:139], v[112:115], off offset:256
	s_mov_b32 s1, 0x900000
	s_mov_b32 s2, s0
	v_lshl_add_u64 v[112:113], v[104:105], 0, v[148:149]
	v_cvt_pk_bf16_f32 v104, v116, v117
	v_cvt_pk_bf16_f32 v105, v118, v119
	v_cvt_pk_bf16_f32 v106, v108, v109
	v_cvt_pk_bf16_f32 v107, v110, v111
	global_store_dwordx4 v[112:113], v[104:107], off
	v_cvt_pk_bf16_f32 v96, v96, v97
	v_cvt_pk_bf16_f32 v97, v98, v99
	v_cvt_pk_bf16_f32 v98, v88, v89
	v_or_b32_e32 v88, 32, v144
	v_ashrrev_i32_e32 v89, 31, v88
	v_lshlrev_b64 v[88:89], 16, v[88:89]
	v_lshl_add_u64 v[88:89], s[20:21], 0, v[88:89]
	v_cvt_pk_bf16_f32 v99, v90, v91
	global_store_dwordx4 v[112:113], v[96:99], off offset:256
	s_mov_b32 s57, s40
	s_mov_b64 s[28:29], s[44:45]
	v_lshl_add_u64 v[96:97], v[88:89], 0, v[148:149]
	v_cvt_pk_bf16_f32 v88, v100, v101
	v_cvt_pk_bf16_f32 v89, v102, v103
	v_cvt_pk_bf16_f32 v90, v92, v93
	v_cvt_pk_bf16_f32 v91, v94, v95
	global_store_dwordx4 v[96:97], v[88:91], off
	v_cvt_pk_bf16_f32 v84, v84, v85
	v_cvt_pk_bf16_f32 v85, v86, v87
	v_cvt_pk_bf16_f32 v86, v76, v77
	v_or_b32_e32 v76, 48, v144
	v_ashrrev_i32_e32 v77, 31, v76
	v_lshlrev_b64 v[76:77], 16, v[76:77]
	v_lshl_add_u64 v[76:77], s[20:21], 0, v[76:77]
	v_cvt_pk_bf16_f32 v87, v78, v79
	global_store_dwordx4 v[96:97], v[84:87], off offset:256
	s_mov_b64 s[20:21], 0x800000
	s_mov_b64 s[46:47], s[42:43]
	v_lshl_add_u64 v[84:85], v[76:77], 0, v[148:149]
	v_cvt_pk_bf16_f32 v76, v80, v81
	v_cvt_pk_bf16_f32 v77, v82, v83
	v_cvt_pk_bf16_f32 v78, v72, v73
	v_cvt_pk_bf16_f32 v79, v74, v75
	global_store_dwordx4 v[84:85], v[76:79], off
	v_cvt_pk_bf16_f32 v68, v68, v69
	v_cvt_pk_bf16_f32 v69, v70, v71
	v_cvt_pk_bf16_f32 v70, v64, v65
	v_cvt_pk_bf16_f32 v71, v66, v67
	global_store_dwordx4 v[84:85], v[68:71], off offset:256
	v_cvt_pk_bf16_f32 v60, v60, v61
	v_cvt_pk_bf16_f32 v61, v62, v63
	v_cvt_pk_bf16_f32 v62, v56, v57
	v_add_co_u32_e32 v56, vcc, s23, v138
	v_lshl_add_u64 v[64:65], v[138:139], 0, s[20:21]
	s_nop 0
	v_addc_co_u32_e32 v57, vcc, 0, v139, vcc
	v_cvt_pk_bf16_f32 v63, v58, v59
	global_store_dwordx4 v[56:57], v[60:63], off
	v_cvt_pk_bf16_f32 v48, v48, v49
	v_cvt_pk_bf16_f32 v49, v50, v51
	v_cvt_pk_bf16_f32 v50, v40, v41
	v_cvt_pk_bf16_f32 v51, v42, v43
	global_store_dwordx4 v[64:65], v[48:51], off offset:256
	s_mov_b64 s[20:21], 0x900000
	v_cvt_pk_bf16_f32 v40, v52, v53
	v_cvt_pk_bf16_f32 v41, v54, v55
	v_cvt_pk_bf16_f32 v42, v44, v45
	v_add_co_u32_e32 v44, vcc, s1, v138
	v_lshl_add_u64 v[48:49], v[138:139], 0, s[20:21]
	s_nop 0
	v_addc_co_u32_e32 v45, vcc, 0, v139, vcc
	s_mov_b32 s1, 0xa00000
	v_cvt_pk_bf16_f32 v43, v46, v47
	global_store_dwordx4 v[44:45], v[40:43], off
	v_cvt_pk_bf16_f32 v32, v32, v33
	v_cvt_pk_bf16_f32 v33, v34, v35
	v_cvt_pk_bf16_f32 v34, v24, v25
	v_cvt_pk_bf16_f32 v35, v26, v27
	global_store_dwordx4 v[48:49], v[32:35], off offset:256
	s_mov_b64 s[20:21], 0xa00000
	v_cvt_pk_bf16_f32 v24, v36, v37
	v_cvt_pk_bf16_f32 v25, v38, v39
	v_cvt_pk_bf16_f32 v26, v28, v29
	v_add_co_u32_e32 v28, vcc, s1, v138
	v_lshl_add_u64 v[32:33], v[138:139], 0, s[20:21]
	s_nop 0
	v_addc_co_u32_e32 v29, vcc, 0, v139, vcc
	s_mov_b32 s1, 0xb00000
	v_cvt_pk_bf16_f32 v27, v30, v31
	global_store_dwordx4 v[28:29], v[24:27], off
	v_cvt_pk_bf16_f32 v16, v16, v17
	v_cvt_pk_bf16_f32 v17, v18, v19
	v_cvt_pk_bf16_f32 v18, v8, v9
	v_cvt_pk_bf16_f32 v19, v10, v11
	global_store_dwordx4 v[32:33], v[16:19], off offset:256
	v_cvt_pk_bf16_f32 v8, v20, v21
	v_cvt_pk_bf16_f32 v9, v22, v23
	v_cvt_pk_bf16_f32 v10, v12, v13
	v_add_co_u32_e32 v12, vcc, s1, v138
	s_mov_b64 s[20:21], 0xb00000
	s_nop 0
	v_addc_co_u32_e32 v13, vcc, 0, v139, vcc
	v_lshl_add_u64 v[16:17], v[138:139], 0, s[20:21]
	s_and_b64 vcc, exec, s[38:39]
	v_cvt_pk_bf16_f32 v11, v14, v15
	global_store_dwordx4 v[12:13], v[8:11], off
	v_cvt_pk_bf16_f32 v4, v4, v5
	v_cvt_pk_bf16_f32 v5, v6, v7
	v_cvt_pk_bf16_f32 v6, v0, v1
	v_cvt_pk_bf16_f32 v7, v2, v3
	global_store_dwordx4 v[16:17], v[4:7], off offset:256
	s_cbranch_vccz .LBB0_285
	s_waitcnt vmcnt(0)
	v_readlane_b32 s54, v253, 37
	s_cmpk_gt_u32 s3, 0xff
	v_readlane_b32 s55, v253, 38
	s_cbranch_scc1 .LBB0_296
	s_barrier

.Lesa7_far:
	s_waitcnt vmcnt(40)
	s_mov_b32 s32, 0
	s_branch .Lesa7_join
.Lesa6_far:
	s_waitcnt vmcnt(24)
	s_mov_b32 s32, 0
	s_branch .Lesa6_join
